# GEMM K-loops: redundant post-barrier lgkmcnt wait and mid-block setprio flip removed, setprio 1 raised before the barrier
# speedup vs baseline: 1.0170x; 1.0053x over previous
; #define PG8_STAGE(bufoff, gbase, voff) do { _Pragma("unroll") for (int _i = 0; _i < 2; ++_i) \
;         __builtin_amdgcn_global_load_lds((const unsigned*)((const char*)(gbase) + (voff)[_i]), (PG8_LAS unsigned*)(lds + (bufoff) + ldsw + _i * 8192), 16, 0, 0); } while (0)
; #define PG8_LDA(dst, b, h) do { _Pragma("unroll") for (int m = 0; m < 4; ++m) _Pragma("unroll") for (int k = 0; k < 2; ++k) dst[m][k] = *(const PG8_LAS bf16x8*)(lds + PG8_SA(b, h) + aoff + m * 2048 + k * 1024); } while (0)
; #define PG8_LDB(dst, b, h) do { _Pragma("unroll") for (int n = 0; n < 2; ++n) _Pragma("unroll") for (int k = 0; k < 2; ++k) dst[n][k] = *(const PG8_LAS bf16x8*)(lds + PG8_SB(b, h) + boff + n * 2048 + k * 1024); } while (0)
; #define PG8_MMA(ai, bj, At, Bt) do { __builtin_amdgcn_s_setprio(1); _Pragma("unroll") for (int m = 0; m < 4; ++m) _Pragma("unroll") for (int n = 0; n < 2; ++n) _Pragma("unroll") for (int k = 0; k < 2; ++k) \
;         acc[ai][bj][m][n] = __builtin_amdgcn_mfma_f32_16x16x32_bf16(Bt[n][k], At[m][k], acc[ai][bj][m][n], 0, 0, 0); __builtin_amdgcn_s_setprio(0); } while (0)
; template <class Epi, class Sched, bool ALIGN_EPI = false, bool SP2 = false>
; __device__ __forceinline__ void gemm_phase(PG8_LAS unsigned char* lds, const Gemm g, const Sched& S, const Epi& E, const int wv) {
;     ...
;             if constexpr (SP2) {
;             PG8_LDB(B0, 0, 0); PG8_LDB(B1, 0, 1); PG8_SCHED; PG8_LDA(At, 0, 0); PG8_STAGE(PG8_SA(1, 1), a1 + hstep, voffA);
;             PG8_WAIT_V(8); PG8_WAIT_L(0); PG8_BAR; PG8_MMA(0, 0, At, B0); PG8_MMA(0, 1, At, B1); PG8_BAR; PG8_SCHED;
;             PG8_LDA(At, 0, 1); PG8_STAGE(PG8_SB(0, 0), b2, voffB); PG8_STAGE(PG8_SB(0, 1), b2 + hstep, voffB); PG8_STAGE(PG8_SA(0, 0), a2, voffA);
;             PG8_WAIT_V(8); PG8_WAIT_L(0); PG8_BAR; PG8_MMA(1, 0, At, B0); PG8_MMA(1, 1, At, B1); PG8_BAR; PG8_SCHED;
;             PG8_LDB(B0, 1, 0); PG8_LDB(B1, 1, 1); PG8_SCHED; PG8_LDA(At, 1, 0); PG8_STAGE(PG8_SA(0, 1), a2 + hstep, voffA);
;             PG8_WAIT_V(8); PG8_WAIT_L(0); PG8_BAR; PG8_MMA(0, 0, At, B0); PG8_MMA(0, 1, At, B1); PG8_BAR; PG8_SCHED;
;             PG8_LDA(At, 1, 1); PG8_STAGE(PG8_SB(1, 0), b3, voffB); PG8_STAGE(PG8_SB(1, 1), b3 + hstep, voffB); PG8_STAGE(PG8_SA(1, 0), a3, voffA);
;             PG8_WAIT_V(8); PG8_WAIT_L(0); PG8_BAR; PG8_MMA(1, 0, At, B0); PG8_MMA(1, 1, At, B1); PG8_BAR; PG8_SCHED;
.LBB0_40:
	s_add_u32 s74, s76, 0xffe00080
	s_addc_u32 s75, s77, -1
	s_add_i32 s82, 0, 0x10000
	s_cmpk_eq_i32 s66, 0x7c
	s_cselect_b32 s81, s34, s75
	s_cselect_b32 s80, s35, s74
	v_add_u32_e32 v146, s82, v154
	s_cselect_b32 s79, s47, s62
	s_cselect_b32 s78, s49, s61
	s_add_i32 s83, 0, 0x14000
	ds_read_b128 v[142:145], v146
	ds_read_b128 v[158:161], v146 offset:1024
	ds_read_b128 v[162:165], v146 offset:2048
	ds_read_b128 v[166:169], v146 offset:3072
	v_add_u32_e32 v146, s83, v154
	ds_read_b128 v[170:173], v146
	ds_read_b128 v[174:177], v146 offset:1024
	ds_read_b128 v[190:193], v146 offset:2048
	ds_read_b128 v[194:197], v146 offset:3072
	v_lshl_add_u64 v[146:147], s[76:77], 0, v[140:141]
	s_add_i32 m0, s14, 0xc000
	ds_read_b128 v[198:201], v156
	ds_read_b128 v[202:205], v156 offset:1024
	ds_read_b128 v[206:209], v156 offset:2048
	ds_read_b128 v[210:213], v156 offset:3072
	ds_read_b128 v[214:217], v156 offset:4096
	ds_read_b128 v[218:221], v156 offset:5120
	ds_read_b128 v[222:225], v156 offset:6144
	ds_read_b128 v[226:229], v156 offset:7168
	global_load_lds_dwordx4 v[146:147], off
	v_lshl_add_u64 v[146:147], s[76:77], 0, v[138:139]
	s_add_i32 m0, s14, 0xe000
	s_nop 0
	global_load_lds_dwordx4 v[146:147], off
	s_waitcnt vmcnt(8)
	s_waitcnt lgkmcnt(0)
	s_setprio 1
	s_barrier
	v_mfma_f32_16x16x32_bf16 v[126:129], v[142:145], v[198:201], v[126:129]
	v_mfma_f32_16x16x32_bf16 v[122:125], v[162:165], v[198:201], v[122:125]
	v_mfma_f32_16x16x32_bf16 v[110:113], v[142:145], v[206:209], v[110:113]
	v_mfma_f32_16x16x32_bf16 v[106:109], v[162:165], v[206:209], v[106:109]
	v_mfma_f32_16x16x32_bf16 v[94:97], v[142:145], v[214:217], v[94:97]
	v_mfma_f32_16x16x32_bf16 v[90:93], v[162:165], v[214:217], v[90:93]
	v_mfma_f32_16x16x32_bf16 v[78:81], v[142:145], v[222:225], v[78:81]
	v_mfma_f32_16x16x32_bf16 v[74:77], v[162:165], v[222:225], v[74:77]
	v_mfma_f32_16x16x32_bf16 v[126:129], v[158:161], v[202:205], v[126:129]
	v_mfma_f32_16x16x32_bf16 v[122:125], v[166:169], v[202:205], v[122:125]
	v_mfma_f32_16x16x32_bf16 v[110:113], v[158:161], v[210:213], v[110:113]
	v_mfma_f32_16x16x32_bf16 v[106:109], v[166:169], v[210:213], v[106:109]
	v_mfma_f32_16x16x32_bf16 v[94:97], v[158:161], v[218:221], v[94:97]
	v_mfma_f32_16x16x32_bf16 v[90:93], v[166:169], v[218:221], v[90:93]
	v_mfma_f32_16x16x32_bf16 v[78:81], v[158:161], v[226:229], v[78:81]
	v_mfma_f32_16x16x32_bf16 v[74:77], v[166:169], v[226:229], v[74:77]
	v_mfma_f32_16x16x32_bf16 v[118:121], v[170:173], v[198:201], v[118:121]
	v_mfma_f32_16x16x32_bf16 v[114:117], v[190:193], v[198:201], v[114:117]
	v_mfma_f32_16x16x32_bf16 v[102:105], v[170:173], v[206:209], v[102:105]
	v_mfma_f32_16x16x32_bf16 v[98:101], v[190:193], v[206:209], v[98:101]
	v_mfma_f32_16x16x32_bf16 v[86:89], v[170:173], v[214:217], v[86:89]
	v_mfma_f32_16x16x32_bf16 v[82:85], v[190:193], v[214:217], v[82:85]
	v_mfma_f32_16x16x32_bf16 v[70:73], v[170:173], v[222:225], v[70:73]
	v_mfma_f32_16x16x32_bf16 v[66:69], v[190:193], v[222:225], v[66:69]
	v_mfma_f32_16x16x32_bf16 v[118:121], v[174:177], v[202:205], v[118:121]
	v_mfma_f32_16x16x32_bf16 v[114:117], v[194:197], v[202:205], v[114:117]
	v_mfma_f32_16x16x32_bf16 v[102:105], v[174:177], v[210:213], v[102:105]
	v_mfma_f32_16x16x32_bf16 v[98:101], v[194:197], v[210:213], v[98:101]
	v_mfma_f32_16x16x32_bf16 v[86:89], v[174:177], v[218:221], v[86:89]
	v_mfma_f32_16x16x32_bf16 v[82:85], v[194:197], v[218:221], v[82:85]
	v_mfma_f32_16x16x32_bf16 v[70:73], v[174:177], v[226:229], v[70:73]
	v_mfma_f32_16x16x32_bf16 v[66:69], v[194:197], v[226:229], v[66:69]
	s_setprio 0
	s_barrier
	s_add_i32 s74, s82, s7
	v_lshl_add_u64 v[146:147], s[78:79], 0, v[134:135]
	s_mov_b32 m0, s74
	ds_read_b128 v[198:201], v156 offset:16384
	ds_read_b128 v[202:205], v156 offset:17408
	ds_read_b128 v[206:209], v156 offset:18432
	ds_read_b128 v[210:213], v156 offset:19456
	ds_read_b128 v[214:217], v156 offset:20480
	ds_read_b128 v[218:221], v156 offset:21504
	ds_read_b128 v[222:225], v156 offset:22528
	ds_read_b128 v[226:229], v156 offset:23552
	global_load_lds_dwordx4 v[146:147], off
	s_add_i32 m0, s74, 0x2000
	s_add_u32 s74, s78, 0x200000
	v_lshl_add_u64 v[148:149], s[78:79], 0, v[130:131]
	s_addc_u32 s75, s79, 0
	s_add_i32 s82, s83, s7
	global_load_lds_dwordx4 v[148:149], off
	v_lshl_add_u64 v[152:153], s[74:75], 0, v[134:135]
	s_mov_b32 m0, s82
	v_lshl_add_u64 v[178:179], s[80:81], 0, v[132:133]
	global_load_lds_dwordx4 v[152:153], off
	v_lshl_add_u64 v[152:153], s[74:75], 0, v[130:131]
	s_add_i32 m0, s82, 0x2000
	s_nop 0
	global_load_lds_dwordx4 v[152:153], off
	v_lshl_add_u64 v[152:153], s[80:81], 0, v[136:137]
	s_mov_b32 m0, s14
	s_nop 0
	global_load_lds_dwordx4 v[152:153], off
	s_mov_b32 m0, s15
	s_nop 0
	global_load_lds_dwordx4 v[178:179], off
	s_waitcnt vmcnt(8)
	s_waitcnt lgkmcnt(0)
	s_setprio 1
	s_barrier
; #define PG8_STAGE(bufoff, gbase, voff) do { _Pragma("unroll") for (int _i = 0; _i < 2; ++_i) \
;         __builtin_amdgcn_global_load_lds((const unsigned*)((const char*)(gbase) + (voff)[_i]), (PG8_LAS unsigned*)(lds + (bufoff) + ldsw + _i * 8192), 16, 0, 0); } while (0)
; #define PG8_LDA(dst, b, h) do { _Pragma("unroll") for (int m = 0; m < 4; ++m) _Pragma("unroll") for (int k = 0; k < 2; ++k) dst[m][k] = *(const PG8_LAS bf16x8*)(lds + PG8_SA(b, h) + aoff + m * 2048 + k * 1024); } while (0)
; #define PG8_LDB(dst, b, h) do { _Pragma("unroll") for (int n = 0; n < 2; ++n) _Pragma("unroll") for (int k = 0; k < 2; ++k) dst[n][k] = *(const PG8_LAS bf16x8*)(lds + PG8_SB(b, h) + boff + n * 2048 + k * 1024); } while (0)
; #define PG8_MMA(ai, bj, At, Bt) do { __builtin_amdgcn_s_setprio(1); _Pragma("unroll") for (int m = 0; m < 4; ++m) _Pragma("unroll") for (int n = 0; n < 2; ++n) _Pragma("unroll") for (int k = 0; k < 2; ++k) \
;         acc[ai][bj][m][n] = __builtin_amdgcn_mfma_f32_16x16x32_bf16(Bt[n][k], At[m][k], acc[ai][bj][m][n], 0, 0, 0); __builtin_amdgcn_s_setprio(0); } while (0)
; template <class Epi, class Sched, bool ALIGN_EPI = false, bool SP2 = false>
; __device__ __forceinline__ void gemm_phase(PG8_LAS unsigned char* lds, const Gemm g, const Sched& S, const Epi& E, const int wv) {
;     ...
;             if constexpr (SP2) {
;             PG8_LDB(B0, 0, 0); PG8_LDB(B1, 0, 1); PG8_SCHED; PG8_LDA(At, 0, 0); PG8_STAGE(PG8_SA(1, 1), a1 + hstep, voffA);
;             PG8_WAIT_V(8); PG8_WAIT_L(0); PG8_BAR; PG8_MMA(0, 0, At, B0); PG8_MMA(0, 1, At, B1); PG8_BAR; PG8_SCHED;
;             PG8_LDA(At, 0, 1); PG8_STAGE(PG8_SB(0, 0), b2, voffB); PG8_STAGE(PG8_SB(0, 1), b2 + hstep, voffB); PG8_STAGE(PG8_SA(0, 0), a2, voffA);
;             PG8_WAIT_V(8); PG8_WAIT_L(0); PG8_BAR; PG8_MMA(1, 0, At, B0); PG8_MMA(1, 1, At, B1); PG8_BAR; PG8_SCHED;
;             PG8_LDB(B0, 1, 0); PG8_LDB(B1, 1, 1); PG8_SCHED; PG8_LDA(At, 1, 0); PG8_STAGE(PG8_SA(0, 1), a2 + hstep, voffA);
;             PG8_WAIT_V(8); PG8_WAIT_L(0); PG8_BAR; PG8_MMA(0, 0, At, B0); PG8_MMA(0, 1, At, B1); PG8_BAR; PG8_SCHED;
;             PG8_LDA(At, 1, 1); PG8_STAGE(PG8_SB(1, 0), b3, voffB); PG8_STAGE(PG8_SB(1, 1), b3 + hstep, voffB); PG8_STAGE(PG8_SA(1, 0), a3, voffA);
;             PG8_WAIT_V(8); PG8_WAIT_L(0); PG8_BAR; PG8_MMA(1, 0, At, B0); PG8_MMA(1, 1, At, B1); PG8_BAR; PG8_SCHED;
	v_mfma_f32_16x16x32_bf16 v[62:65], v[142:145], v[198:201], v[62:65]
	v_mfma_f32_16x16x32_bf16 v[58:61], v[162:165], v[198:201], v[58:61]
	v_mfma_f32_16x16x32_bf16 v[46:49], v[142:145], v[206:209], v[46:49]
	v_mfma_f32_16x16x32_bf16 v[42:45], v[162:165], v[206:209], v[42:45]
	v_mfma_f32_16x16x32_bf16 v[30:33], v[142:145], v[214:217], v[30:33]
	v_mfma_f32_16x16x32_bf16 v[26:29], v[162:165], v[214:217], v[26:29]
	v_mfma_f32_16x16x32_bf16 v[14:17], v[142:145], v[222:225], v[14:17]
	v_mfma_f32_16x16x32_bf16 v[10:13], v[162:165], v[222:225], v[10:13]
	v_mfma_f32_16x16x32_bf16 v[62:65], v[158:161], v[202:205], v[62:65]
	v_mfma_f32_16x16x32_bf16 v[58:61], v[166:169], v[202:205], v[58:61]
	v_mfma_f32_16x16x32_bf16 v[46:49], v[158:161], v[210:213], v[46:49]
	v_mfma_f32_16x16x32_bf16 v[42:45], v[166:169], v[210:213], v[42:45]
	v_mfma_f32_16x16x32_bf16 v[30:33], v[158:161], v[218:221], v[30:33]
	v_mfma_f32_16x16x32_bf16 v[26:29], v[166:169], v[218:221], v[26:29]
	v_mfma_f32_16x16x32_bf16 v[14:17], v[158:161], v[226:229], v[14:17]
	v_mfma_f32_16x16x32_bf16 v[10:13], v[166:169], v[226:229], v[10:13]
	v_mfma_f32_16x16x32_bf16 v[54:57], v[170:173], v[198:201], v[54:57]
	v_mfma_f32_16x16x32_bf16 v[50:53], v[190:193], v[198:201], v[50:53]
	v_mfma_f32_16x16x32_bf16 v[38:41], v[170:173], v[206:209], v[38:41]
	v_mfma_f32_16x16x32_bf16 v[34:37], v[190:193], v[206:209], v[34:37]
	v_mfma_f32_16x16x32_bf16 v[22:25], v[170:173], v[214:217], v[22:25]
	v_mfma_f32_16x16x32_bf16 v[18:21], v[190:193], v[214:217], v[18:21]
	v_mfma_f32_16x16x32_bf16 v[6:9], v[170:173], v[222:225], v[6:9]
	v_mfma_f32_16x16x32_bf16 v[2:5], v[190:193], v[222:225], v[2:5]
	v_mfma_f32_16x16x32_bf16 v[54:57], v[174:177], v[202:205], v[54:57]
	v_mfma_f32_16x16x32_bf16 v[50:53], v[194:197], v[202:205], v[50:53]
	v_mfma_f32_16x16x32_bf16 v[38:41], v[174:177], v[210:213], v[38:41]
	v_mfma_f32_16x16x32_bf16 v[34:37], v[194:197], v[210:213], v[34:37]
	v_mfma_f32_16x16x32_bf16 v[22:25], v[174:177], v[218:221], v[22:25]
	v_mfma_f32_16x16x32_bf16 v[18:21], v[194:197], v[218:221], v[18:21]
	v_mfma_f32_16x16x32_bf16 v[6:9], v[174:177], v[226:229], v[6:9]
	v_mfma_f32_16x16x32_bf16 v[2:5], v[194:197], v[226:229], v[2:5]
	s_setprio 0
	s_barrier
	s_add_i32 s82, 0, 0x18000
	v_add_u32_e32 v157, s82, v154
	s_add_i32 s83, 0, 0x1c000
	ds_read_b128 v[142:145], v157
	ds_read_b128 v[158:161], v157 offset:1024
	ds_read_b128 v[162:165], v157 offset:2048
	ds_read_b128 v[166:169], v157 offset:3072
	v_add_u32_e32 v157, s83, v154
	ds_read_b128 v[170:173], v157
	ds_read_b128 v[174:177], v157 offset:1024
	ds_read_b128 v[190:193], v157 offset:2048
	ds_read_b128 v[194:197], v157 offset:3072
	s_add_u32 s74, s80, 0x200000
	s_addc_u32 s75, s81, 0
	s_mov_b32 m0, s16
	v_lshl_add_u64 v[230:231], s[74:75], 0, v[136:137]
	ds_read_b128 v[198:201], v156 offset:32768
	ds_read_b128 v[202:205], v156 offset:33792
	ds_read_b128 v[206:209], v156 offset:34816
	ds_read_b128 v[210:213], v156 offset:35840
	ds_read_b128 v[214:217], v156 offset:36864
	ds_read_b128 v[218:221], v156 offset:37888
	ds_read_b128 v[222:225], v156 offset:38912
	ds_read_b128 v[226:229], v156 offset:39936
	global_load_lds_dwordx4 v[230:231], off
	v_lshl_add_u64 v[230:231], s[74:75], 0, v[132:133]
	s_mov_b32 m0, s17
	s_nop 0
	global_load_lds_dwordx4 v[230:231], off
	s_waitcnt vmcnt(8)
	s_waitcnt lgkmcnt(0)
	s_setprio 1
	s_barrier
	v_mfma_f32_16x16x32_bf16 v[126:129], v[142:145], v[198:201], v[126:129]
	v_mfma_f32_16x16x32_bf16 v[122:125], v[162:165], v[198:201], v[122:125]
	v_mfma_f32_16x16x32_bf16 v[110:113], v[142:145], v[206:209], v[110:113]
	v_mfma_f32_16x16x32_bf16 v[106:109], v[162:165], v[206:209], v[106:109]
	v_mfma_f32_16x16x32_bf16 v[94:97], v[142:145], v[214:217], v[94:97]
	v_mfma_f32_16x16x32_bf16 v[90:93], v[162:165], v[214:217], v[90:93]
	v_mfma_f32_16x16x32_bf16 v[78:81], v[142:145], v[222:225], v[78:81]
	v_mfma_f32_16x16x32_bf16 v[74:77], v[162:165], v[222:225], v[74:77]
	v_mfma_f32_16x16x32_bf16 v[126:129], v[158:161], v[202:205], v[126:129]
	v_mfma_f32_16x16x32_bf16 v[122:125], v[166:169], v[202:205], v[122:125]
	v_mfma_f32_16x16x32_bf16 v[110:113], v[158:161], v[210:213], v[110:113]
	v_mfma_f32_16x16x32_bf16 v[106:109], v[166:169], v[210:213], v[106:109]
	v_mfma_f32_16x16x32_bf16 v[94:97], v[158:161], v[218:221], v[94:97]
	v_mfma_f32_16x16x32_bf16 v[90:93], v[166:169], v[218:221], v[90:93]
	v_mfma_f32_16x16x32_bf16 v[78:81], v[158:161], v[226:229], v[78:81]
	v_mfma_f32_16x16x32_bf16 v[74:77], v[166:169], v[226:229], v[74:77]
	v_mfma_f32_16x16x32_bf16 v[118:121], v[170:173], v[198:201], v[118:121]
	v_mfma_f32_16x16x32_bf16 v[114:117], v[190:193], v[198:201], v[114:117]
	v_mfma_f32_16x16x32_bf16 v[102:105], v[170:173], v[206:209], v[102:105]
	v_mfma_f32_16x16x32_bf16 v[98:101], v[190:193], v[206:209], v[98:101]
	v_mfma_f32_16x16x32_bf16 v[86:89], v[170:173], v[214:217], v[86:89]
	v_mfma_f32_16x16x32_bf16 v[82:85], v[190:193], v[214:217], v[82:85]
	v_mfma_f32_16x16x32_bf16 v[70:73], v[170:173], v[222:225], v[70:73]
	v_mfma_f32_16x16x32_bf16 v[66:69], v[190:193], v[222:225], v[66:69]
	v_mfma_f32_16x16x32_bf16 v[118:121], v[174:177], v[202:205], v[118:121]
	v_mfma_f32_16x16x32_bf16 v[114:117], v[194:197], v[202:205], v[114:117]
	v_mfma_f32_16x16x32_bf16 v[102:105], v[174:177], v[210:213], v[102:105]
	v_mfma_f32_16x16x32_bf16 v[98:101], v[194:197], v[210:213], v[98:101]
	v_mfma_f32_16x16x32_bf16 v[86:89], v[174:177], v[218:221], v[86:89]
	v_mfma_f32_16x16x32_bf16 v[82:85], v[194:197], v[218:221], v[82:85]
	v_mfma_f32_16x16x32_bf16 v[70:73], v[174:177], v[226:229], v[70:73]
	v_mfma_f32_16x16x32_bf16 v[66:69], v[194:197], v[226:229], v[66:69]
	s_setprio 0
	s_barrier
; #define PG8_STAGE(bufoff, gbase, voff) do { _Pragma("unroll") for (int _i = 0; _i < 2; ++_i) \
;         __builtin_amdgcn_global_load_lds((const unsigned*)((const char*)(gbase) + (voff)[_i]), (PG8_LAS unsigned*)(lds + (bufoff) + ldsw + _i * 8192), 16, 0, 0); } while (0)
; #define PG8_LDA(dst, b, h) do { _Pragma("unroll") for (int m = 0; m < 4; ++m) _Pragma("unroll") for (int k = 0; k < 2; ++k) dst[m][k] = *(const PG8_LAS bf16x8*)(lds + PG8_SA(b, h) + aoff + m * 2048 + k * 1024); } while (0)
; #define PG8_LDB(dst, b, h) do { _Pragma("unroll") for (int n = 0; n < 2; ++n) _Pragma("unroll") for (int k = 0; k < 2; ++k) dst[n][k] = *(const PG8_LAS bf16x8*)(lds + PG8_SB(b, h) + boff + n * 2048 + k * 1024); } while (0)
; #define PG8_MMA(ai, bj, At, Bt) do { __builtin_amdgcn_s_setprio(1); _Pragma("unroll") for (int m = 0; m < 4; ++m) _Pragma("unroll") for (int n = 0; n < 2; ++n) _Pragma("unroll") for (int k = 0; k < 2; ++k) \
;         acc[ai][bj][m][n] = __builtin_amdgcn_mfma_f32_16x16x32_bf16(Bt[n][k], At[m][k], acc[ai][bj][m][n], 0, 0, 0); __builtin_amdgcn_s_setprio(0); } while (0)
; template <class Epi, class Sched, bool ALIGN_EPI = false, bool SP2 = false>
; __device__ __forceinline__ void gemm_phase(PG8_LAS unsigned char* lds, const Gemm g, const Sched& S, const Epi& E, const int wv) {
;     ...
;             if constexpr (SP2) {
;             PG8_LDB(B0, 0, 0); PG8_LDB(B1, 0, 1); PG8_SCHED; PG8_LDA(At, 0, 0); PG8_STAGE(PG8_SA(1, 1), a1 + hstep, voffA);
;             PG8_WAIT_V(8); PG8_WAIT_L(0); PG8_BAR; PG8_MMA(0, 0, At, B0); PG8_MMA(0, 1, At, B1); PG8_BAR; PG8_SCHED;
;             PG8_LDA(At, 0, 1); PG8_STAGE(PG8_SB(0, 0), b2, voffB); PG8_STAGE(PG8_SB(0, 1), b2 + hstep, voffB); PG8_STAGE(PG8_SA(0, 0), a2, voffA);
;             PG8_WAIT_V(8); PG8_WAIT_L(0); PG8_BAR; PG8_MMA(1, 0, At, B0); PG8_MMA(1, 1, At, B1); PG8_BAR; PG8_SCHED;
;             PG8_LDB(B0, 1, 0); PG8_LDB(B1, 1, 1); PG8_SCHED; PG8_LDA(At, 1, 0); PG8_STAGE(PG8_SA(0, 1), a2 + hstep, voffA);
;             PG8_WAIT_V(8); PG8_WAIT_L(0); PG8_BAR; PG8_MMA(0, 0, At, B0); PG8_MMA(0, 1, At, B1); PG8_BAR; PG8_SCHED;
;             PG8_LDA(At, 1, 1); PG8_STAGE(PG8_SB(1, 0), b3, voffB); PG8_STAGE(PG8_SB(1, 1), b3 + hstep, voffB); PG8_STAGE(PG8_SA(1, 0), a3, voffA);
;             PG8_WAIT_V(8); PG8_WAIT_L(0); PG8_BAR; PG8_MMA(1, 0, At, B0); PG8_MMA(1, 1, At, B1); PG8_BAR; PG8_SCHED;
	s_add_i32 s74, s82, s7
	v_lshl_add_u64 v[146:147], v[146:147], 0, s[26:27]
	s_mov_b32 m0, s74
	ds_read_b128 v[198:201], v156 offset:49152
	ds_read_b128 v[202:205], v156 offset:50176
	ds_read_b128 v[206:209], v156 offset:51200
	ds_read_b128 v[210:213], v156 offset:52224
	ds_read_b128 v[214:217], v156 offset:53248
	ds_read_b128 v[218:221], v156 offset:54272
	ds_read_b128 v[222:225], v156 offset:55296
	ds_read_b128 v[226:229], v156 offset:56320
	global_load_lds_dwordx4 v[146:147], off
	s_add_i32 m0, s74, 0x2000
	s_add_u32 s74, s78, 0x200080
	v_lshl_add_u64 v[146:147], v[148:149], 0, s[26:27]
	s_addc_u32 s75, s79, 0
	s_add_i32 s78, s83, s7
	global_load_lds_dwordx4 v[146:147], off
	v_lshl_add_u64 v[146:147], s[74:75], 0, v[134:135]
	s_mov_b32 m0, s78
	s_nop 0
	global_load_lds_dwordx4 v[146:147], off
	v_lshl_add_u64 v[146:147], s[74:75], 0, v[130:131]
	s_add_i32 m0, s78, 0x2000
	s_nop 0
	global_load_lds_dwordx4 v[146:147], off
	v_lshl_add_u64 v[146:147], v[152:153], 0, s[26:27]
	s_mov_b32 m0, s22
	s_nop 0
	global_load_lds_dwordx4 v[146:147], off
	v_lshl_add_u64 v[146:147], v[178:179], 0, s[26:27]
	s_mov_b32 m0, s23
	s_nop 0
	global_load_lds_dwordx4 v[146:147], off
	s_waitcnt vmcnt(8)
	s_waitcnt lgkmcnt(0)
	s_setprio 1
	s_barrier
	v_mfma_f32_16x16x32_bf16 v[62:65], v[142:145], v[198:201], v[62:65]
	v_mfma_f32_16x16x32_bf16 v[58:61], v[162:165], v[198:201], v[58:61]
	v_mfma_f32_16x16x32_bf16 v[46:49], v[142:145], v[206:209], v[46:49]
	v_mfma_f32_16x16x32_bf16 v[42:45], v[162:165], v[206:209], v[42:45]
	v_mfma_f32_16x16x32_bf16 v[30:33], v[142:145], v[214:217], v[30:33]
	v_mfma_f32_16x16x32_bf16 v[26:29], v[162:165], v[214:217], v[26:29]
	v_mfma_f32_16x16x32_bf16 v[14:17], v[142:145], v[222:225], v[14:17]
	v_mfma_f32_16x16x32_bf16 v[10:13], v[162:165], v[222:225], v[10:13]
	v_mfma_f32_16x16x32_bf16 v[62:65], v[158:161], v[202:205], v[62:65]
	v_mfma_f32_16x16x32_bf16 v[58:61], v[166:169], v[202:205], v[58:61]
	v_mfma_f32_16x16x32_bf16 v[46:49], v[158:161], v[210:213], v[46:49]
	v_mfma_f32_16x16x32_bf16 v[42:45], v[166:169], v[210:213], v[42:45]
	v_mfma_f32_16x16x32_bf16 v[30:33], v[158:161], v[218:221], v[30:33]
	v_mfma_f32_16x16x32_bf16 v[26:29], v[166:169], v[218:221], v[26:29]
	v_mfma_f32_16x16x32_bf16 v[14:17], v[158:161], v[226:229], v[14:17]
	v_mfma_f32_16x16x32_bf16 v[10:13], v[166:169], v[226:229], v[10:13]
	v_mfma_f32_16x16x32_bf16 v[54:57], v[170:173], v[198:201], v[54:57]
	v_mfma_f32_16x16x32_bf16 v[50:53], v[190:193], v[198:201], v[50:53]
	v_mfma_f32_16x16x32_bf16 v[38:41], v[170:173], v[206:209], v[38:41]
	v_mfma_f32_16x16x32_bf16 v[34:37], v[190:193], v[206:209], v[34:37]
	v_mfma_f32_16x16x32_bf16 v[22:25], v[170:173], v[214:217], v[22:25]
	v_mfma_f32_16x16x32_bf16 v[18:21], v[190:193], v[214:217], v[18:21]
	v_mfma_f32_16x16x32_bf16 v[6:9], v[170:173], v[222:225], v[6:9]
	v_mfma_f32_16x16x32_bf16 v[2:5], v[190:193], v[222:225], v[2:5]
	v_mfma_f32_16x16x32_bf16 v[54:57], v[174:177], v[202:205], v[54:57]
	v_mfma_f32_16x16x32_bf16 v[50:53], v[194:197], v[202:205], v[50:53]
	v_mfma_f32_16x16x32_bf16 v[38:41], v[174:177], v[210:213], v[38:41]
	v_mfma_f32_16x16x32_bf16 v[34:37], v[194:197], v[210:213], v[34:37]
	v_mfma_f32_16x16x32_bf16 v[22:25], v[174:177], v[218:221], v[22:25]
	v_mfma_f32_16x16x32_bf16 v[18:21], v[194:197], v[218:221], v[18:21]
	v_mfma_f32_16x16x32_bf16 v[6:9], v[174:177], v[226:229], v[6:9]
	v_mfma_f32_16x16x32_bf16 v[2:5], v[194:197], v[226:229], v[2:5]
	s_setprio 0
	s_barrier
	s_add_i32 s66, s66, 2
	s_add_u32 s61, s61, 0x100
	s_addc_u32 s62, s62, 0
	s_add_u32 s76, s76, 0x100
	s_addc_u32 s77, s77, 0
	s_cmpk_gt_u32 s66, 0x7d
	s_cbranch_scc0 .LBB0_40
	s_and_b64 vcc, exec, s[8:9]
	s_cbranch_vccz .LBB0_43
	s_barrier

; #define PG8_STAGE(bufoff, gbase, voff) do { _Pragma("unroll") for (int _i = 0; _i < 2; ++_i) \
;         __builtin_amdgcn_global_load_lds((const unsigned*)((const char*)(gbase) + (voff)[_i]), (PG8_LAS unsigned*)(lds + (bufoff) + ldsw + _i * 8192), 16, 0, 0); } while (0)
; #define PG8_LDA(dst, b, h) do { _Pragma("unroll") for (int m = 0; m < 4; ++m) _Pragma("unroll") for (int k = 0; k < 2; ++k) dst[m][k] = *(const PG8_LAS bf16x8*)(lds + PG8_SA(b, h) + aoff + m * 2048 + k * 1024); } while (0)
; template <class Epi, class Sched, bool ALIGN_EPI = false, bool SP2 = false>
; __device__ __forceinline__ void gemm_phase(PG8_LAS unsigned char* lds, const Gemm g, const Sched& S, const Epi& E, const int wv) {
;     ...
;         const char* nA = has_next ? (const char*)g.A + (size_t)nxt.pm * tstep + (size_t)nxt.pk * K * 2 : cA; const char* nB = has_next ? (const char*)g.Bt + (size_t)nxt.pn * tstep + (size_t)nxt.pk * K * 2 : cB;
;         for (int t = 0; t < nt; t += 2) {
;             const bool last = (t == nt - 2);
;             const char* a1 = cA + (size_t)(t + 1) * kstep;
;             const char* a2 = last ? nA : cA + (size_t)(t + 2) * kstep; const char* b2 = last ? nB : cB + (size_t)(t + 2) * kstep;
;             const char* a3 = a2 + kstep; const char* b3 = b2 + kstep;
;             if (last && has_next) S.a_ready(nxt);
;             if constexpr (SP2) {
;             PG8_LDB(B0, 0, 0); PG8_LDB(B1, 0, 1); PG8_SCHED; PG8_LDA(At, 0, 0); PG8_STAGE(PG8_SA(1, 1), a1 + hstep, voffA);
;             PG8_WAIT_V(8); PG8_WAIT_L(0); PG8_BAR; PG8_MMA(0, 0, At, B0); PG8_MMA(0, 1, At, B1); PG8_BAR; PG8_SCHED;
;             PG8_LDA(At, 0, 1); PG8_STAGE(PG8_SB(0, 0), b2, voffB); PG8_STAGE(PG8_SB(0, 1), b2 + hstep, voffB); PG8_STAGE(PG8_SA(0, 0), a2, voffA);
;             PG8_WAIT_V(8); PG8_WAIT_L(0); PG8_BAR; PG8_MMA(1, 0, At, B0); PG8_MMA(1, 1, At, B1); PG8_BAR; PG8_SCHED;
;             PG8_LDB(B0, 1, 0); PG8_LDB(B1, 1, 1); PG8_SCHED; PG8_LDA(At, 1, 0); PG8_STAGE(PG8_SA(0, 1), a2 + hstep, voffA);
;             PG8_WAIT_V(8); PG8_WAIT_L(0); PG8_BAR; PG8_MMA(0, 0, At, B0); PG8_MMA(0, 1, At, B1); PG8_BAR; PG8_SCHED;
;             PG8_LDA(At, 1, 1); PG8_STAGE(PG8_SB(1, 0), b3, voffB); PG8_STAGE(PG8_SB(1, 1), b3 + hstep, voffB); PG8_STAGE(PG8_SA(1, 0), a3, voffA);
;             PG8_WAIT_V(8); PG8_WAIT_L(0); PG8_BAR; PG8_MMA(1, 0, At, B0); PG8_MMA(1, 1, At, B1); PG8_BAR; PG8_SCHED;
.LBB0_60:
	s_add_u32 s62, s48, s34
	s_addc_u32 s66, s49, 0
	s_add_u32 s35, s62, 0x100
	s_addc_u32 s71, s66, 0
	s_and_b64 s[74:75], s[84:85], exec
	s_cselect_b32 s89, s1, s71
	s_cselect_b32 s88, s0, s35
	s_add_u32 s34, s46, s34
	s_addc_u32 s35, s47, 0
	s_add_u32 s71, s34, 0x100
	s_addc_u32 s74, s35, 0
	s_add_i32 s77, 0, 0x10000
	s_and_b64 s[34:35], s[84:85], exec
	s_cselect_b32 s91, s81, s74
	s_cselect_b32 s90, s80, s71
	s_add_i32 s71, 0, 0x14000
	s_add_u32 s74, s62, 0x200080
	s_addc_u32 s75, s66, 0
	s_add_i32 s66, s77, s7
	s_add_i32 m0, s14, 0xc000
	s_add_i32 s62, s14, 0xe000
	s_add_i32 s79, s66, 0x2000
	s_add_u32 vcc_lo, s90, 0x200000
	v_add_u32_e32 v90, s77, v0
	v_add_u32_e32 v106, s71, v0
	s_addc_u32 vcc_hi, s91, 0
	s_add_i32 s97, s71, s7
	ds_read_b128 v[78:81], v90
	ds_read_b128 v[82:85], v90 offset:1024
	ds_read_b128 v[86:89], v90 offset:2048
	ds_read_b128 v[90:93], v90 offset:3072
	ds_read_b128 v[94:97], v106
	s_waitcnt lgkmcnt(0)
	ds_read_b128 v[98:101], v106 offset:1024
	ds_read_b128 v[102:105], v106 offset:2048
	ds_read_b128 v[106:109], v106 offset:3072
	s_add_i32 s40, s97, 0x2000
	s_add_i32 s35, 0, 0x18000
	s_add_i32 s43, 0, 0x1c000
	s_add_u32 s86, s88, 0x200000
	s_addc_u32 s87, s89, 0
	s_add_i32 s34, s35, s7
	s_add_i32 s42, s34, 0x2000
	s_add_u32 s84, s90, 0x200080
	s_addc_u32 s85, s91, 0
	s_add_i32 s71, s43, s7
	s_add_i32 s77, s71, 0x2000
	v_lshl_add_u64 v[142:143], s[74:75], 0, v[72:73]
	ds_read_b128 v[110:113], v77
	ds_read_b128 v[114:117], v77 offset:1024
	ds_read_b128 v[118:121], v77 offset:2048
	ds_read_b128 v[122:125], v77 offset:3072
	ds_read_b128 v[126:129], v77 offset:4096
	ds_read_b128 v[130:133], v77 offset:5120
	ds_read_b128 v[134:137], v77 offset:6144
	ds_read_b128 v[138:141], v77 offset:7168
	global_load_lds_dwordx4 v[142:143], off
	v_lshl_add_u64 v[142:143], s[74:75], 0, v[68:69]
	s_mov_b32 m0, s62
	s_nop 0
	global_load_lds_dwordx4 v[142:143], off
	s_waitcnt vmcnt(8)
	s_waitcnt lgkmcnt(0)
	s_setprio 1
	s_barrier
	v_mfma_f32_16x16x32_bf16 v[62:65], v[78:81], v[110:113], v[62:65]
	v_mfma_f32_16x16x32_bf16 v[58:61], v[86:89], v[110:113], v[58:61]
	v_mfma_f32_16x16x32_bf16 v[54:57], v[78:81], v[118:121], v[54:57]
	v_mfma_f32_16x16x32_bf16 v[50:53], v[86:89], v[118:121], v[50:53]
	v_mfma_f32_16x16x32_bf16 v[38:41], v[78:81], v[126:129], v[38:41]
	v_mfma_f32_16x16x32_bf16 v[34:37], v[86:89], v[126:129], v[34:37]
	v_mfma_f32_16x16x32_bf16 v[22:25], v[78:81], v[134:137], v[22:25]
	v_mfma_f32_16x16x32_bf16 v[18:21], v[86:89], v[134:137], v[18:21]
	v_mfma_f32_16x16x32_bf16 v[62:65], v[82:85], v[114:117], v[62:65]
	v_mfma_f32_16x16x32_bf16 v[58:61], v[90:93], v[114:117], v[58:61]
	v_mfma_f32_16x16x32_bf16 v[54:57], v[82:85], v[122:125], v[54:57]
	v_mfma_f32_16x16x32_bf16 v[50:53], v[90:93], v[122:125], v[50:53]
	v_mfma_f32_16x16x32_bf16 v[38:41], v[82:85], v[130:133], v[38:41]
	v_mfma_f32_16x16x32_bf16 v[34:37], v[90:93], v[130:133], v[34:37]
	v_mfma_f32_16x16x32_bf16 v[22:25], v[82:85], v[138:141], v[22:25]
	v_mfma_f32_16x16x32_bf16 v[18:21], v[90:93], v[138:141], v[18:21]
	v_mfma_f32_16x16x32_bf16 v[46:49], v[94:97], v[110:113], v[46:49]
	v_mfma_f32_16x16x32_bf16 v[42:45], v[102:105], v[110:113], v[42:45]
	v_mfma_f32_16x16x32_bf16 v[30:33], v[94:97], v[118:121], v[30:33]
	v_mfma_f32_16x16x32_bf16 v[26:29], v[102:105], v[118:121], v[26:29]
	v_mfma_f32_16x16x32_bf16 v[14:17], v[94:97], v[126:129], v[14:17]
	v_mfma_f32_16x16x32_bf16 v[10:13], v[102:105], v[126:129], v[10:13]
	v_mfma_f32_16x16x32_bf16 v[6:9], v[94:97], v[134:137], v[6:9]
	v_mfma_f32_16x16x32_bf16 v[2:5], v[102:105], v[134:137], v[2:5]
	v_mfma_f32_16x16x32_bf16 v[46:49], v[98:101], v[114:117], v[46:49]
	v_mfma_f32_16x16x32_bf16 v[42:45], v[106:109], v[114:117], v[42:45]
	v_mfma_f32_16x16x32_bf16 v[30:33], v[98:101], v[122:125], v[30:33]
	v_mfma_f32_16x16x32_bf16 v[26:29], v[106:109], v[122:125], v[26:29]
	v_mfma_f32_16x16x32_bf16 v[14:17], v[98:101], v[130:133], v[14:17]
	v_mfma_f32_16x16x32_bf16 v[10:13], v[106:109], v[130:133], v[10:13]
	v_mfma_f32_16x16x32_bf16 v[6:9], v[98:101], v[138:141], v[6:9]
	v_mfma_f32_16x16x32_bf16 v[2:5], v[106:109], v[138:141], v[2:5]
	s_setprio 0
	s_barrier
	s_mov_b32 m0, s66
	v_lshl_add_u64 v[142:143], s[90:91], 0, v[70:71]
	global_load_lds_dwordx4 v[142:143], off
	v_lshl_add_u64 v[144:145], s[90:91], 0, v[66:67]
	s_mov_b32 m0, s79
	v_lshl_add_u64 v[78:79], vcc, 0, v[70:71]
	global_load_lds_dwordx4 v[144:145], off
	s_mov_b32 m0, s97
	v_lshl_add_u64 v[146:147], s[88:89], 0, v[72:73]
	global_load_lds_dwordx4 v[78:79], off
	v_lshl_add_u64 v[78:79], vcc, 0, v[66:67]
	s_mov_b32 m0, s40
	v_lshl_add_u64 v[148:149], s[88:89], 0, v[68:69]
	global_load_lds_dwordx4 v[78:79], off
	s_mov_b32 m0, s14
	s_nop 0
	global_load_lds_dwordx4 v[146:147], off
	s_mov_b32 m0, s17
	s_nop 0
	global_load_lds_dwordx4 v[148:149], off
	s_waitcnt vmcnt(8)
	s_waitcnt lgkmcnt(0)
	s_barrier
; #define PG8_STAGE(bufoff, gbase, voff) do { _Pragma("unroll") for (int _i = 0; _i < 2; ++_i) \
;         __builtin_amdgcn_global_load_lds((const unsigned*)((const char*)(gbase) + (voff)[_i]), (PG8_LAS unsigned*)(lds + (bufoff) + ldsw + _i * 8192), 16, 0, 0); } while (0)
; #define PG8_LDA(dst, b, h) do { _Pragma("unroll") for (int m = 0; m < 4; ++m) _Pragma("unroll") for (int k = 0; k < 2; ++k) dst[m][k] = *(const PG8_LAS bf16x8*)(lds + PG8_SA(b, h) + aoff + m * 2048 + k * 1024); } while (0)
; #define PG8_LDB(dst, b, h) do { _Pragma("unroll") for (int n = 0; n < 2; ++n) _Pragma("unroll") for (int k = 0; k < 2; ++k) dst[n][k] = *(const PG8_LAS bf16x8*)(lds + PG8_SB(b, h) + boff + n * 2048 + k * 1024); } while (0)
; #define PG8_MMA(ai, bj, At, Bt) do { __builtin_amdgcn_s_setprio(1); _Pragma("unroll") for (int m = 0; m < 4; ++m) _Pragma("unroll") for (int n = 0; n < 2; ++n) _Pragma("unroll") for (int k = 0; k < 2; ++k) \
;         acc[ai][bj][m][n] = __builtin_amdgcn_mfma_f32_16x16x32_bf16(Bt[n][k], At[m][k], acc[ai][bj][m][n], 0, 0, 0); __builtin_amdgcn_s_setprio(0); } while (0)
; template <class Epi, class Sched, bool ALIGN_EPI = false, bool SP2 = false>
; __device__ __forceinline__ void gemm_phase(PG8_LAS unsigned char* lds, const Gemm g, const Sched& S, const Epi& E, const int wv) {
;     ...
;             if constexpr (SP2) {
;             PG8_LDB(B0, 0, 0); PG8_LDB(B1, 0, 1); PG8_SCHED; PG8_LDA(At, 0, 0); PG8_STAGE(PG8_SA(1, 1), a1 + hstep, voffA);
;             PG8_WAIT_V(8); PG8_WAIT_L(0); PG8_BAR; PG8_MMA(0, 0, At, B0); PG8_MMA(0, 1, At, B1); PG8_BAR; PG8_SCHED;
;             PG8_LDA(At, 0, 1); PG8_STAGE(PG8_SB(0, 0), b2, voffB); PG8_STAGE(PG8_SB(0, 1), b2 + hstep, voffB); PG8_STAGE(PG8_SA(0, 0), a2, voffA);
;             PG8_WAIT_V(8); PG8_WAIT_L(0); PG8_BAR; PG8_MMA(1, 0, At, B0); PG8_MMA(1, 1, At, B1); PG8_BAR; PG8_SCHED;
;             PG8_LDB(B0, 1, 0); PG8_LDB(B1, 1, 1); PG8_SCHED; PG8_LDA(At, 1, 0); PG8_STAGE(PG8_SA(0, 1), a2 + hstep, voffA);
;             PG8_WAIT_V(8); PG8_WAIT_L(0); PG8_BAR; PG8_MMA(0, 0, At, B0); PG8_MMA(0, 1, At, B1); PG8_BAR; PG8_SCHED;
;             PG8_LDA(At, 1, 1); PG8_STAGE(PG8_SB(1, 0), b3, voffB); PG8_STAGE(PG8_SB(1, 1), b3 + hstep, voffB); PG8_STAGE(PG8_SA(1, 0), a3, voffA);
;             PG8_WAIT_V(8); PG8_WAIT_L(0); PG8_BAR; PG8_MMA(1, 0, At, B0); PG8_MMA(1, 1, At, B1); PG8_BAR; PG8_SCHED;
	s_setprio 1
	s_setprio 0
	s_setprio 1
	s_setprio 0
	s_barrier
	v_add_u32_e32 v90, s35, v0
	v_add_u32_e32 v106, s43, v0
	ds_read_b128 v[78:81], v90
	ds_read_b128 v[82:85], v90 offset:1024
	ds_read_b128 v[86:89], v90 offset:2048
	ds_read_b128 v[90:93], v90 offset:3072
	ds_read_b128 v[94:97], v106
	ds_read_b128 v[98:101], v106 offset:1024
	ds_read_b128 v[102:105], v106 offset:2048
	ds_read_b128 v[106:109], v106 offset:3072
	s_mov_b32 m0, s22
	v_lshl_add_u64 v[152:153], s[86:87], 0, v[72:73]
	ds_read_b128 v[110:113], v77 offset:32768
	ds_read_b128 v[114:117], v77 offset:33792
	ds_read_b128 v[118:121], v77 offset:34816
	ds_read_b128 v[122:125], v77 offset:35840
	ds_read_b128 v[126:129], v77 offset:36864
	ds_read_b128 v[130:133], v77 offset:37888
	ds_read_b128 v[134:137], v77 offset:38912
	ds_read_b128 v[138:141], v77 offset:39936
	global_load_lds_dwordx4 v[152:153], off
	v_lshl_add_u64 v[152:153], s[86:87], 0, v[68:69]
	s_mov_b32 m0, s23
	s_nop 0
	global_load_lds_dwordx4 v[152:153], off
	s_waitcnt vmcnt(8)
	s_waitcnt lgkmcnt(0)
	s_setprio 1
	s_barrier
	v_mfma_f32_16x16x32_bf16 v[62:65], v[78:81], v[110:113], v[62:65]
	v_mfma_f32_16x16x32_bf16 v[58:61], v[86:89], v[110:113], v[58:61]
	v_mfma_f32_16x16x32_bf16 v[54:57], v[78:81], v[118:121], v[54:57]
	v_mfma_f32_16x16x32_bf16 v[50:53], v[86:89], v[118:121], v[50:53]
	v_mfma_f32_16x16x32_bf16 v[38:41], v[78:81], v[126:129], v[38:41]
	v_mfma_f32_16x16x32_bf16 v[34:37], v[86:89], v[126:129], v[34:37]
	v_mfma_f32_16x16x32_bf16 v[22:25], v[78:81], v[134:137], v[22:25]
	v_mfma_f32_16x16x32_bf16 v[18:21], v[86:89], v[134:137], v[18:21]
	v_mfma_f32_16x16x32_bf16 v[62:65], v[82:85], v[114:117], v[62:65]
	v_mfma_f32_16x16x32_bf16 v[58:61], v[90:93], v[114:117], v[58:61]
	v_mfma_f32_16x16x32_bf16 v[54:57], v[82:85], v[122:125], v[54:57]
	v_mfma_f32_16x16x32_bf16 v[50:53], v[90:93], v[122:125], v[50:53]
	v_mfma_f32_16x16x32_bf16 v[38:41], v[82:85], v[130:133], v[38:41]
	v_mfma_f32_16x16x32_bf16 v[34:37], v[90:93], v[130:133], v[34:37]
	v_mfma_f32_16x16x32_bf16 v[22:25], v[82:85], v[138:141], v[22:25]
	v_mfma_f32_16x16x32_bf16 v[18:21], v[90:93], v[138:141], v[18:21]
	v_mfma_f32_16x16x32_bf16 v[46:49], v[94:97], v[110:113], v[46:49]
	v_mfma_f32_16x16x32_bf16 v[42:45], v[102:105], v[110:113], v[42:45]
	v_mfma_f32_16x16x32_bf16 v[30:33], v[94:97], v[118:121], v[30:33]
	v_mfma_f32_16x16x32_bf16 v[26:29], v[102:105], v[118:121], v[26:29]
	v_mfma_f32_16x16x32_bf16 v[14:17], v[94:97], v[126:129], v[14:17]
	v_mfma_f32_16x16x32_bf16 v[10:13], v[102:105], v[126:129], v[10:13]
	v_mfma_f32_16x16x32_bf16 v[6:9], v[94:97], v[134:137], v[6:9]
	v_mfma_f32_16x16x32_bf16 v[2:5], v[102:105], v[134:137], v[2:5]
	v_mfma_f32_16x16x32_bf16 v[46:49], v[98:101], v[114:117], v[46:49]
	v_mfma_f32_16x16x32_bf16 v[42:45], v[106:109], v[114:117], v[42:45]
	v_mfma_f32_16x16x32_bf16 v[30:33], v[98:101], v[122:125], v[30:33]
	v_mfma_f32_16x16x32_bf16 v[26:29], v[106:109], v[122:125], v[26:29]
	v_mfma_f32_16x16x32_bf16 v[14:17], v[98:101], v[130:133], v[14:17]
	v_mfma_f32_16x16x32_bf16 v[10:13], v[106:109], v[130:133], v[10:13]
	v_mfma_f32_16x16x32_bf16 v[6:9], v[98:101], v[138:141], v[6:9]
	v_mfma_f32_16x16x32_bf16 v[2:5], v[106:109], v[138:141], v[2:5]
	s_setprio 0
	s_barrier
	s_mov_b32 m0, s34
	v_lshl_add_u64 v[78:79], v[142:143], 0, s[26:27]
	global_load_lds_dwordx4 v[78:79], off
	v_lshl_add_u64 v[78:79], v[144:145], 0, s[26:27]
	s_mov_b32 m0, s42
	s_nop 0
	global_load_lds_dwordx4 v[78:79], off
	v_lshl_add_u64 v[78:79], s[84:85], 0, v[70:71]
	s_mov_b32 m0, s71
	s_nop 0
	global_load_lds_dwordx4 v[78:79], off
	v_lshl_add_u64 v[78:79], s[84:85], 0, v[66:67]
	s_mov_b32 m0, s77
	s_nop 0
	global_load_lds_dwordx4 v[78:79], off
	v_lshl_add_u64 v[78:79], v[146:147], 0, s[26:27]
	s_mov_b32 m0, s41
	s_nop 0
	global_load_lds_dwordx4 v[78:79], off
	v_lshl_add_u64 v[78:79], v[148:149], 0, s[26:27]
	s_mov_b32 m0, s57
	s_nop 0
	global_load_lds_dwordx4 v[78:79], off
	s_waitcnt vmcnt(8)
	s_waitcnt lgkmcnt(0)
	s_barrier
	s_setprio 1
	s_setprio 0
	s_setprio 1
	s_setprio 0
	s_barrier
	s_movk_i32 s34, 0x100
	s_andn2_b64 vcc, exec, s[82:83]
	s_mov_b64 s[84:85], -1
	s_mov_b64 s[82:83], 0
	s_cbranch_vccz .LBB0_60
	s_and_b64 vcc, exec, s[68:69]
	s_cbranch_vccz .LBB0_63
	s_barrier

; #define PG8_STAGE(bufoff, gbase, voff) do { _Pragma("unroll") for (int _i = 0; _i < 2; ++_i) \
;         __builtin_amdgcn_global_load_lds((const unsigned*)((const char*)(gbase) + (voff)[_i]), (PG8_LAS unsigned*)(lds + (bufoff) + ldsw + _i * 8192), 16, 0, 0); } while (0)
; #define PG8_LDA(dst, b, h) do { _Pragma("unroll") for (int m = 0; m < 4; ++m) _Pragma("unroll") for (int k = 0; k < 2; ++k) dst[m][k] = *(const PG8_LAS bf16x8*)(lds + PG8_SA(b, h) + aoff + m * 2048 + k * 1024); } while (0)
; #define PG8_LDB(dst, b, h) do { _Pragma("unroll") for (int n = 0; n < 2; ++n) _Pragma("unroll") for (int k = 0; k < 2; ++k) dst[n][k] = *(const PG8_LAS bf16x8*)(lds + PG8_SB(b, h) + boff + n * 2048 + k * 1024); } while (0)
; #define PG8_MMA(ai, bj, At, Bt) do { __builtin_amdgcn_s_setprio(1); _Pragma("unroll") for (int m = 0; m < 4; ++m) _Pragma("unroll") for (int n = 0; n < 2; ++n) _Pragma("unroll") for (int k = 0; k < 2; ++k) \
;         acc[ai][bj][m][n] = __builtin_amdgcn_mfma_f32_16x16x32_bf16(Bt[n][k], At[m][k], acc[ai][bj][m][n], 0, 0, 0); __builtin_amdgcn_s_setprio(0); } while (0)
; template <class Epi, class Sched, bool ALIGN_EPI = false, bool SP2 = false>
; __device__ __forceinline__ void gemm_phase(PG8_LAS unsigned char* lds, const Gemm g, const Sched& S, const Epi& E, const int wv) {
;     ...
;             if constexpr (SP2) {
;             PG8_LDB(B0, 0, 0); PG8_LDB(B1, 0, 1); PG8_SCHED; PG8_LDA(At, 0, 0); PG8_STAGE(PG8_SA(1, 1), a1 + hstep, voffA);
;             PG8_WAIT_V(8); PG8_WAIT_L(0); PG8_BAR; PG8_MMA(0, 0, At, B0); PG8_MMA(0, 1, At, B1); PG8_BAR; PG8_SCHED;
;             PG8_LDA(At, 0, 1); PG8_STAGE(PG8_SB(0, 0), b2, voffB); PG8_STAGE(PG8_SB(0, 1), b2 + hstep, voffB); PG8_STAGE(PG8_SA(0, 0), a2, voffA);
;             PG8_WAIT_V(8); PG8_WAIT_L(0); PG8_BAR; PG8_MMA(1, 0, At, B0); PG8_MMA(1, 1, At, B1); PG8_BAR; PG8_SCHED;
;             PG8_LDB(B0, 1, 0); PG8_LDB(B1, 1, 1); PG8_SCHED; PG8_LDA(At, 1, 0); PG8_STAGE(PG8_SA(0, 1), a2 + hstep, voffA);
;             PG8_WAIT_V(8); PG8_WAIT_L(0); PG8_BAR; PG8_MMA(0, 0, At, B0); PG8_MMA(0, 1, At, B1); PG8_BAR; PG8_SCHED;
;             PG8_LDA(At, 1, 1); PG8_STAGE(PG8_SB(1, 0), b3, voffB); PG8_STAGE(PG8_SB(1, 1), b3 + hstep, voffB); PG8_STAGE(PG8_SA(1, 0), a3, voffA);
;             PG8_WAIT_V(8); PG8_WAIT_L(0); PG8_BAR; PG8_MMA(1, 0, At, B0); PG8_MMA(1, 1, At, B1); PG8_BAR; PG8_SCHED;
.LBB0_78:
	s_add_u32 s74, s76, 0xfff80080
	s_addc_u32 s75, s77, -1
	s_add_i32 s82, 0, 0x10000
	s_cmp_eq_u32 s66, 28
	s_cselect_b32 s81, s34, s75
	s_cselect_b32 s80, s35, s74
	v_add_u32_e32 v145, s82, v142
	s_cselect_b32 s79, s47, s62
	s_cselect_b32 s78, s49, s61
	s_add_i32 s83, 0, 0x14000
	ds_read_b128 v[152:155], v145
	ds_read_b128 v[156:159], v145 offset:1024
	ds_read_b128 v[160:163], v145 offset:2048
	ds_read_b128 v[164:167], v145 offset:3072
	v_add_u32_e32 v145, s83, v142
	ds_read_b128 v[168:171], v145
	ds_read_b128 v[172:175], v145 offset:1024
	ds_read_b128 v[176:179], v145 offset:2048
	ds_read_b128 v[190:193], v145 offset:3072
	v_lshl_add_u64 v[146:147], s[76:77], 0, v[140:141]
	s_add_i32 m0, s14, 0xc000
	ds_read_b128 v[194:197], v144
	ds_read_b128 v[198:201], v144 offset:1024
	ds_read_b128 v[202:205], v144 offset:2048
	ds_read_b128 v[206:209], v144 offset:3072
	ds_read_b128 v[210:213], v144 offset:4096
	ds_read_b128 v[214:217], v144 offset:5120
	ds_read_b128 v[218:221], v144 offset:6144
	ds_read_b128 v[222:225], v144 offset:7168
	global_load_lds_dwordx4 v[146:147], off
	v_lshl_add_u64 v[146:147], s[76:77], 0, v[138:139]
	s_add_i32 m0, s14, 0xe000
	s_nop 0
	global_load_lds_dwordx4 v[146:147], off
	s_waitcnt vmcnt(8)
	s_waitcnt lgkmcnt(0)
	s_setprio 1
	s_barrier
	v_mfma_f32_16x16x32_bf16 v[126:129], v[152:155], v[194:197], v[126:129]
	v_mfma_f32_16x16x32_bf16 v[122:125], v[160:163], v[194:197], v[122:125]
	v_mfma_f32_16x16x32_bf16 v[110:113], v[152:155], v[202:205], v[110:113]
	v_mfma_f32_16x16x32_bf16 v[106:109], v[160:163], v[202:205], v[106:109]
	v_mfma_f32_16x16x32_bf16 v[94:97], v[152:155], v[210:213], v[94:97]
	v_mfma_f32_16x16x32_bf16 v[90:93], v[160:163], v[210:213], v[90:93]
	v_mfma_f32_16x16x32_bf16 v[78:81], v[152:155], v[218:221], v[78:81]
	v_mfma_f32_16x16x32_bf16 v[74:77], v[160:163], v[218:221], v[74:77]
	v_mfma_f32_16x16x32_bf16 v[126:129], v[156:159], v[198:201], v[126:129]
	v_mfma_f32_16x16x32_bf16 v[122:125], v[164:167], v[198:201], v[122:125]
	v_mfma_f32_16x16x32_bf16 v[110:113], v[156:159], v[206:209], v[110:113]
	v_mfma_f32_16x16x32_bf16 v[106:109], v[164:167], v[206:209], v[106:109]
	v_mfma_f32_16x16x32_bf16 v[94:97], v[156:159], v[214:217], v[94:97]
	v_mfma_f32_16x16x32_bf16 v[90:93], v[164:167], v[214:217], v[90:93]
	v_mfma_f32_16x16x32_bf16 v[78:81], v[156:159], v[222:225], v[78:81]
	v_mfma_f32_16x16x32_bf16 v[74:77], v[164:167], v[222:225], v[74:77]
	v_mfma_f32_16x16x32_bf16 v[118:121], v[168:171], v[194:197], v[118:121]
	v_mfma_f32_16x16x32_bf16 v[114:117], v[176:179], v[194:197], v[114:117]
	v_mfma_f32_16x16x32_bf16 v[102:105], v[168:171], v[202:205], v[102:105]
	v_mfma_f32_16x16x32_bf16 v[98:101], v[176:179], v[202:205], v[98:101]
	v_mfma_f32_16x16x32_bf16 v[86:89], v[168:171], v[210:213], v[86:89]
	v_mfma_f32_16x16x32_bf16 v[82:85], v[176:179], v[210:213], v[82:85]
	v_mfma_f32_16x16x32_bf16 v[70:73], v[168:171], v[218:221], v[70:73]
	v_mfma_f32_16x16x32_bf16 v[66:69], v[176:179], v[218:221], v[66:69]
	v_mfma_f32_16x16x32_bf16 v[118:121], v[172:175], v[198:201], v[118:121]
	v_mfma_f32_16x16x32_bf16 v[114:117], v[190:193], v[198:201], v[114:117]
	v_mfma_f32_16x16x32_bf16 v[102:105], v[172:175], v[206:209], v[102:105]
	v_mfma_f32_16x16x32_bf16 v[98:101], v[190:193], v[206:209], v[98:101]
	v_mfma_f32_16x16x32_bf16 v[86:89], v[172:175], v[214:217], v[86:89]
	v_mfma_f32_16x16x32_bf16 v[82:85], v[190:193], v[214:217], v[82:85]
	v_mfma_f32_16x16x32_bf16 v[70:73], v[172:175], v[222:225], v[70:73]
	v_mfma_f32_16x16x32_bf16 v[66:69], v[190:193], v[222:225], v[66:69]
	s_setprio 0
	s_barrier
	s_add_i32 s74, s82, s7
	v_lshl_add_u64 v[146:147], s[78:79], 0, v[134:135]
	s_mov_b32 m0, s74
	ds_read_b128 v[194:197], v144 offset:16384
	ds_read_b128 v[198:201], v144 offset:17408
	ds_read_b128 v[202:205], v144 offset:18432
	ds_read_b128 v[206:209], v144 offset:19456
	ds_read_b128 v[210:213], v144 offset:20480
	ds_read_b128 v[214:217], v144 offset:21504
	ds_read_b128 v[218:221], v144 offset:22528
	ds_read_b128 v[222:225], v144 offset:23552
	global_load_lds_dwordx4 v[146:147], off
	s_add_i32 m0, s74, 0x2000
	s_add_u32 s74, s78, 0x80000
	v_lshl_add_u64 v[148:149], s[78:79], 0, v[130:131]
	s_addc_u32 s75, s79, 0
	s_add_i32 s82, s83, s7
	global_load_lds_dwordx4 v[148:149], off
	v_lshl_add_u64 v[226:227], s[74:75], 0, v[134:135]
	s_mov_b32 m0, s82
	v_lshl_add_u64 v[228:229], s[80:81], 0, v[132:133]
	global_load_lds_dwordx4 v[226:227], off
	v_lshl_add_u64 v[226:227], s[74:75], 0, v[130:131]
	s_add_i32 m0, s82, 0x2000
	s_nop 0
	global_load_lds_dwordx4 v[226:227], off
	v_lshl_add_u64 v[226:227], s[80:81], 0, v[136:137]
	s_mov_b32 m0, s14
	s_nop 0
	global_load_lds_dwordx4 v[226:227], off
	s_mov_b32 m0, s15
	s_nop 0
	global_load_lds_dwordx4 v[228:229], off
	s_waitcnt vmcnt(8)
	s_waitcnt lgkmcnt(0)
	s_setprio 1
	s_barrier
; #define PG8_STAGE(bufoff, gbase, voff) do { _Pragma("unroll") for (int _i = 0; _i < 2; ++_i) \
;         __builtin_amdgcn_global_load_lds((const unsigned*)((const char*)(gbase) + (voff)[_i]), (PG8_LAS unsigned*)(lds + (bufoff) + ldsw + _i * 8192), 16, 0, 0); } while (0)
; #define PG8_LDA(dst, b, h) do { _Pragma("unroll") for (int m = 0; m < 4; ++m) _Pragma("unroll") for (int k = 0; k < 2; ++k) dst[m][k] = *(const PG8_LAS bf16x8*)(lds + PG8_SA(b, h) + aoff + m * 2048 + k * 1024); } while (0)
; #define PG8_LDB(dst, b, h) do { _Pragma("unroll") for (int n = 0; n < 2; ++n) _Pragma("unroll") for (int k = 0; k < 2; ++k) dst[n][k] = *(const PG8_LAS bf16x8*)(lds + PG8_SB(b, h) + boff + n * 2048 + k * 1024); } while (0)
; #define PG8_MMA(ai, bj, At, Bt) do { __builtin_amdgcn_s_setprio(1); _Pragma("unroll") for (int m = 0; m < 4; ++m) _Pragma("unroll") for (int n = 0; n < 2; ++n) _Pragma("unroll") for (int k = 0; k < 2; ++k) \
;         acc[ai][bj][m][n] = __builtin_amdgcn_mfma_f32_16x16x32_bf16(Bt[n][k], At[m][k], acc[ai][bj][m][n], 0, 0, 0); __builtin_amdgcn_s_setprio(0); } while (0)
; template <class Epi, class Sched, bool ALIGN_EPI = false, bool SP2 = false>
; __device__ __forceinline__ void gemm_phase(PG8_LAS unsigned char* lds, const Gemm g, const Sched& S, const Epi& E, const int wv) {
;     ...
;             if constexpr (SP2) {
;             PG8_LDB(B0, 0, 0); PG8_LDB(B1, 0, 1); PG8_SCHED; PG8_LDA(At, 0, 0); PG8_STAGE(PG8_SA(1, 1), a1 + hstep, voffA);
;             PG8_WAIT_V(8); PG8_WAIT_L(0); PG8_BAR; PG8_MMA(0, 0, At, B0); PG8_MMA(0, 1, At, B1); PG8_BAR; PG8_SCHED;
;             PG8_LDA(At, 0, 1); PG8_STAGE(PG8_SB(0, 0), b2, voffB); PG8_STAGE(PG8_SB(0, 1), b2 + hstep, voffB); PG8_STAGE(PG8_SA(0, 0), a2, voffA);
;             PG8_WAIT_V(8); PG8_WAIT_L(0); PG8_BAR; PG8_MMA(1, 0, At, B0); PG8_MMA(1, 1, At, B1); PG8_BAR; PG8_SCHED;
;             PG8_LDB(B0, 1, 0); PG8_LDB(B1, 1, 1); PG8_SCHED; PG8_LDA(At, 1, 0); PG8_STAGE(PG8_SA(0, 1), a2 + hstep, voffA);
;             PG8_WAIT_V(8); PG8_WAIT_L(0); PG8_BAR; PG8_MMA(0, 0, At, B0); PG8_MMA(0, 1, At, B1); PG8_BAR; PG8_SCHED;
;             PG8_LDA(At, 1, 1); PG8_STAGE(PG8_SB(1, 0), b3, voffB); PG8_STAGE(PG8_SB(1, 1), b3 + hstep, voffB); PG8_STAGE(PG8_SA(1, 0), a3, voffA);
;             PG8_WAIT_V(8); PG8_WAIT_L(0); PG8_BAR; PG8_MMA(1, 0, At, B0); PG8_MMA(1, 1, At, B1); PG8_BAR; PG8_SCHED;
	v_mfma_f32_16x16x32_bf16 v[62:65], v[152:155], v[194:197], v[62:65]
	v_mfma_f32_16x16x32_bf16 v[58:61], v[160:163], v[194:197], v[58:61]
	v_mfma_f32_16x16x32_bf16 v[46:49], v[152:155], v[202:205], v[46:49]
	v_mfma_f32_16x16x32_bf16 v[42:45], v[160:163], v[202:205], v[42:45]
	v_mfma_f32_16x16x32_bf16 v[30:33], v[152:155], v[210:213], v[30:33]
	v_mfma_f32_16x16x32_bf16 v[26:29], v[160:163], v[210:213], v[26:29]
	v_mfma_f32_16x16x32_bf16 v[14:17], v[152:155], v[218:221], v[14:17]
	v_mfma_f32_16x16x32_bf16 v[10:13], v[160:163], v[218:221], v[10:13]
	v_mfma_f32_16x16x32_bf16 v[62:65], v[156:159], v[198:201], v[62:65]
	v_mfma_f32_16x16x32_bf16 v[58:61], v[164:167], v[198:201], v[58:61]
	v_mfma_f32_16x16x32_bf16 v[46:49], v[156:159], v[206:209], v[46:49]
	v_mfma_f32_16x16x32_bf16 v[42:45], v[164:167], v[206:209], v[42:45]
	v_mfma_f32_16x16x32_bf16 v[30:33], v[156:159], v[214:217], v[30:33]
	v_mfma_f32_16x16x32_bf16 v[26:29], v[164:167], v[214:217], v[26:29]
	v_mfma_f32_16x16x32_bf16 v[14:17], v[156:159], v[222:225], v[14:17]
	v_mfma_f32_16x16x32_bf16 v[10:13], v[164:167], v[222:225], v[10:13]
	v_mfma_f32_16x16x32_bf16 v[54:57], v[168:171], v[194:197], v[54:57]
	v_mfma_f32_16x16x32_bf16 v[50:53], v[176:179], v[194:197], v[50:53]
	v_mfma_f32_16x16x32_bf16 v[38:41], v[168:171], v[202:205], v[38:41]
	v_mfma_f32_16x16x32_bf16 v[34:37], v[176:179], v[202:205], v[34:37]
	v_mfma_f32_16x16x32_bf16 v[22:25], v[168:171], v[210:213], v[22:25]
	v_mfma_f32_16x16x32_bf16 v[18:21], v[176:179], v[210:213], v[18:21]
	v_mfma_f32_16x16x32_bf16 v[6:9], v[168:171], v[218:221], v[6:9]
	v_mfma_f32_16x16x32_bf16 v[2:5], v[176:179], v[218:221], v[2:5]
	v_mfma_f32_16x16x32_bf16 v[54:57], v[172:175], v[198:201], v[54:57]
	v_mfma_f32_16x16x32_bf16 v[50:53], v[190:193], v[198:201], v[50:53]
	v_mfma_f32_16x16x32_bf16 v[38:41], v[172:175], v[206:209], v[38:41]
	v_mfma_f32_16x16x32_bf16 v[34:37], v[190:193], v[206:209], v[34:37]
	v_mfma_f32_16x16x32_bf16 v[22:25], v[172:175], v[214:217], v[22:25]
	v_mfma_f32_16x16x32_bf16 v[18:21], v[190:193], v[214:217], v[18:21]
	v_mfma_f32_16x16x32_bf16 v[6:9], v[172:175], v[222:225], v[6:9]
	v_mfma_f32_16x16x32_bf16 v[2:5], v[190:193], v[222:225], v[2:5]
	s_setprio 0
	s_barrier
	s_add_i32 s82, 0, 0x18000
	v_add_u32_e32 v145, s82, v142
	s_add_i32 s83, 0, 0x1c000
	ds_read_b128 v[152:155], v145
	ds_read_b128 v[156:159], v145 offset:1024
	ds_read_b128 v[160:163], v145 offset:2048
	ds_read_b128 v[164:167], v145 offset:3072
	v_add_u32_e32 v145, s83, v142
	ds_read_b128 v[168:171], v145
	ds_read_b128 v[172:175], v145 offset:1024
	ds_read_b128 v[176:179], v145 offset:2048
	ds_read_b128 v[190:193], v145 offset:3072
	s_add_u32 s74, s80, 0x80000
	s_addc_u32 s75, s81, 0
	s_mov_b32 m0, s16
	v_lshl_add_u64 v[230:231], s[74:75], 0, v[136:137]
	ds_read_b128 v[194:197], v144 offset:32768
	ds_read_b128 v[198:201], v144 offset:33792
	ds_read_b128 v[202:205], v144 offset:34816
	ds_read_b128 v[206:209], v144 offset:35840
	ds_read_b128 v[210:213], v144 offset:36864
	ds_read_b128 v[214:217], v144 offset:37888
	ds_read_b128 v[218:221], v144 offset:38912
	ds_read_b128 v[222:225], v144 offset:39936
	global_load_lds_dwordx4 v[230:231], off
	v_lshl_add_u64 v[230:231], s[74:75], 0, v[132:133]
	s_mov_b32 m0, s17
	s_nop 0
	global_load_lds_dwordx4 v[230:231], off
	s_waitcnt vmcnt(8)
	s_waitcnt lgkmcnt(0)
	s_setprio 1
	s_barrier
	v_mfma_f32_16x16x32_bf16 v[126:129], v[152:155], v[194:197], v[126:129]
	v_mfma_f32_16x16x32_bf16 v[122:125], v[160:163], v[194:197], v[122:125]
	v_mfma_f32_16x16x32_bf16 v[110:113], v[152:155], v[202:205], v[110:113]
	v_mfma_f32_16x16x32_bf16 v[106:109], v[160:163], v[202:205], v[106:109]
	v_mfma_f32_16x16x32_bf16 v[94:97], v[152:155], v[210:213], v[94:97]
	v_mfma_f32_16x16x32_bf16 v[90:93], v[160:163], v[210:213], v[90:93]
	v_mfma_f32_16x16x32_bf16 v[78:81], v[152:155], v[218:221], v[78:81]
	v_mfma_f32_16x16x32_bf16 v[74:77], v[160:163], v[218:221], v[74:77]
	v_mfma_f32_16x16x32_bf16 v[126:129], v[156:159], v[198:201], v[126:129]
	v_mfma_f32_16x16x32_bf16 v[122:125], v[164:167], v[198:201], v[122:125]
	v_mfma_f32_16x16x32_bf16 v[110:113], v[156:159], v[206:209], v[110:113]
	v_mfma_f32_16x16x32_bf16 v[106:109], v[164:167], v[206:209], v[106:109]
	v_mfma_f32_16x16x32_bf16 v[94:97], v[156:159], v[214:217], v[94:97]
	v_mfma_f32_16x16x32_bf16 v[90:93], v[164:167], v[214:217], v[90:93]
	v_mfma_f32_16x16x32_bf16 v[78:81], v[156:159], v[222:225], v[78:81]
	v_mfma_f32_16x16x32_bf16 v[74:77], v[164:167], v[222:225], v[74:77]
	v_mfma_f32_16x16x32_bf16 v[118:121], v[168:171], v[194:197], v[118:121]
	v_mfma_f32_16x16x32_bf16 v[114:117], v[176:179], v[194:197], v[114:117]
	v_mfma_f32_16x16x32_bf16 v[102:105], v[168:171], v[202:205], v[102:105]
	v_mfma_f32_16x16x32_bf16 v[98:101], v[176:179], v[202:205], v[98:101]
	v_mfma_f32_16x16x32_bf16 v[86:89], v[168:171], v[210:213], v[86:89]
	v_mfma_f32_16x16x32_bf16 v[82:85], v[176:179], v[210:213], v[82:85]
	v_mfma_f32_16x16x32_bf16 v[70:73], v[168:171], v[218:221], v[70:73]
	v_mfma_f32_16x16x32_bf16 v[66:69], v[176:179], v[218:221], v[66:69]
	v_mfma_f32_16x16x32_bf16 v[118:121], v[172:175], v[198:201], v[118:121]
	v_mfma_f32_16x16x32_bf16 v[114:117], v[190:193], v[198:201], v[114:117]
	v_mfma_f32_16x16x32_bf16 v[102:105], v[172:175], v[206:209], v[102:105]
	v_mfma_f32_16x16x32_bf16 v[98:101], v[190:193], v[206:209], v[98:101]
	v_mfma_f32_16x16x32_bf16 v[86:89], v[172:175], v[214:217], v[86:89]
	v_mfma_f32_16x16x32_bf16 v[82:85], v[190:193], v[214:217], v[82:85]
	v_mfma_f32_16x16x32_bf16 v[70:73], v[172:175], v[222:225], v[70:73]
	v_mfma_f32_16x16x32_bf16 v[66:69], v[190:193], v[222:225], v[66:69]
	s_setprio 0
	s_barrier
; #define PG8_STAGE(bufoff, gbase, voff) do { _Pragma("unroll") for (int _i = 0; _i < 2; ++_i) \
;         __builtin_amdgcn_global_load_lds((const unsigned*)((const char*)(gbase) + (voff)[_i]), (PG8_LAS unsigned*)(lds + (bufoff) + ldsw + _i * 8192), 16, 0, 0); } while (0)
; #define PG8_LDA(dst, b, h) do { _Pragma("unroll") for (int m = 0; m < 4; ++m) _Pragma("unroll") for (int k = 0; k < 2; ++k) dst[m][k] = *(const PG8_LAS bf16x8*)(lds + PG8_SA(b, h) + aoff + m * 2048 + k * 1024); } while (0)
; #define PG8_LDB(dst, b, h) do { _Pragma("unroll") for (int n = 0; n < 2; ++n) _Pragma("unroll") for (int k = 0; k < 2; ++k) dst[n][k] = *(const PG8_LAS bf16x8*)(lds + PG8_SB(b, h) + boff + n * 2048 + k * 1024); } while (0)
; #define PG8_MMA(ai, bj, At, Bt) do { __builtin_amdgcn_s_setprio(1); _Pragma("unroll") for (int m = 0; m < 4; ++m) _Pragma("unroll") for (int n = 0; n < 2; ++n) _Pragma("unroll") for (int k = 0; k < 2; ++k) \
;         acc[ai][bj][m][n] = __builtin_amdgcn_mfma_f32_16x16x32_bf16(Bt[n][k], At[m][k], acc[ai][bj][m][n], 0, 0, 0); __builtin_amdgcn_s_setprio(0); } while (0)
; template <class Epi, class Sched, bool ALIGN_EPI = false, bool SP2 = false>
; __device__ __forceinline__ void gemm_phase(PG8_LAS unsigned char* lds, const Gemm g, const Sched& S, const Epi& E, const int wv) {
;     ...
;             if constexpr (SP2) {
;             PG8_LDB(B0, 0, 0); PG8_LDB(B1, 0, 1); PG8_SCHED; PG8_LDA(At, 0, 0); PG8_STAGE(PG8_SA(1, 1), a1 + hstep, voffA);
;             PG8_WAIT_V(8); PG8_WAIT_L(0); PG8_BAR; PG8_MMA(0, 0, At, B0); PG8_MMA(0, 1, At, B1); PG8_BAR; PG8_SCHED;
;             PG8_LDA(At, 0, 1); PG8_STAGE(PG8_SB(0, 0), b2, voffB); PG8_STAGE(PG8_SB(0, 1), b2 + hstep, voffB); PG8_STAGE(PG8_SA(0, 0), a2, voffA);
;             PG8_WAIT_V(8); PG8_WAIT_L(0); PG8_BAR; PG8_MMA(1, 0, At, B0); PG8_MMA(1, 1, At, B1); PG8_BAR; PG8_SCHED;
;             PG8_LDB(B0, 1, 0); PG8_LDB(B1, 1, 1); PG8_SCHED; PG8_LDA(At, 1, 0); PG8_STAGE(PG8_SA(0, 1), a2 + hstep, voffA);
;             PG8_WAIT_V(8); PG8_WAIT_L(0); PG8_BAR; PG8_MMA(0, 0, At, B0); PG8_MMA(0, 1, At, B1); PG8_BAR; PG8_SCHED;
;             PG8_LDA(At, 1, 1); PG8_STAGE(PG8_SB(1, 0), b3, voffB); PG8_STAGE(PG8_SB(1, 1), b3 + hstep, voffB); PG8_STAGE(PG8_SA(1, 0), a3, voffA);
;             PG8_WAIT_V(8); PG8_WAIT_L(0); PG8_BAR; PG8_MMA(1, 0, At, B0); PG8_MMA(1, 1, At, B1); PG8_BAR; PG8_SCHED;
	s_add_i32 s74, s82, s7
	v_lshl_add_u64 v[146:147], v[146:147], 0, s[26:27]
	s_mov_b32 m0, s74
	ds_read_b128 v[194:197], v144 offset:49152
	ds_read_b128 v[198:201], v144 offset:50176
	ds_read_b128 v[202:205], v144 offset:51200
	ds_read_b128 v[206:209], v144 offset:52224
	ds_read_b128 v[210:213], v144 offset:53248
	ds_read_b128 v[214:217], v144 offset:54272
	ds_read_b128 v[218:221], v144 offset:55296
	ds_read_b128 v[222:225], v144 offset:56320
	global_load_lds_dwordx4 v[146:147], off
	s_add_i32 m0, s74, 0x2000
	s_add_u32 s74, s78, 0x80080
	v_lshl_add_u64 v[146:147], v[148:149], 0, s[26:27]
	s_addc_u32 s75, s79, 0
	s_add_i32 s78, s83, s7
	global_load_lds_dwordx4 v[146:147], off
	v_lshl_add_u64 v[146:147], s[74:75], 0, v[134:135]
	s_mov_b32 m0, s78
	s_nop 0
	global_load_lds_dwordx4 v[146:147], off
	v_lshl_add_u64 v[146:147], s[74:75], 0, v[130:131]
	s_add_i32 m0, s78, 0x2000
	s_nop 0
	global_load_lds_dwordx4 v[146:147], off
	v_lshl_add_u64 v[146:147], v[226:227], 0, s[26:27]
	s_mov_b32 m0, s22
	s_nop 0
	global_load_lds_dwordx4 v[146:147], off
	v_lshl_add_u64 v[146:147], v[228:229], 0, s[26:27]
	s_mov_b32 m0, s23
	s_nop 0
	global_load_lds_dwordx4 v[146:147], off
	s_waitcnt vmcnt(8)
	s_waitcnt lgkmcnt(0)
	s_setprio 1
	s_barrier
	v_mfma_f32_16x16x32_bf16 v[62:65], v[152:155], v[194:197], v[62:65]
	v_mfma_f32_16x16x32_bf16 v[58:61], v[160:163], v[194:197], v[58:61]
	v_mfma_f32_16x16x32_bf16 v[46:49], v[152:155], v[202:205], v[46:49]
	v_mfma_f32_16x16x32_bf16 v[42:45], v[160:163], v[202:205], v[42:45]
	v_mfma_f32_16x16x32_bf16 v[30:33], v[152:155], v[210:213], v[30:33]
	v_mfma_f32_16x16x32_bf16 v[26:29], v[160:163], v[210:213], v[26:29]
	v_mfma_f32_16x16x32_bf16 v[14:17], v[152:155], v[218:221], v[14:17]
	v_mfma_f32_16x16x32_bf16 v[10:13], v[160:163], v[218:221], v[10:13]
	v_mfma_f32_16x16x32_bf16 v[62:65], v[156:159], v[198:201], v[62:65]
	v_mfma_f32_16x16x32_bf16 v[58:61], v[164:167], v[198:201], v[58:61]
	v_mfma_f32_16x16x32_bf16 v[46:49], v[156:159], v[206:209], v[46:49]
	v_mfma_f32_16x16x32_bf16 v[42:45], v[164:167], v[206:209], v[42:45]
	v_mfma_f32_16x16x32_bf16 v[30:33], v[156:159], v[214:217], v[30:33]
	v_mfma_f32_16x16x32_bf16 v[26:29], v[164:167], v[214:217], v[26:29]
	v_mfma_f32_16x16x32_bf16 v[14:17], v[156:159], v[222:225], v[14:17]
	v_mfma_f32_16x16x32_bf16 v[10:13], v[164:167], v[222:225], v[10:13]
	v_mfma_f32_16x16x32_bf16 v[54:57], v[168:171], v[194:197], v[54:57]
	v_mfma_f32_16x16x32_bf16 v[50:53], v[176:179], v[194:197], v[50:53]
	v_mfma_f32_16x16x32_bf16 v[38:41], v[168:171], v[202:205], v[38:41]
	v_mfma_f32_16x16x32_bf16 v[34:37], v[176:179], v[202:205], v[34:37]
	v_mfma_f32_16x16x32_bf16 v[22:25], v[168:171], v[210:213], v[22:25]
	v_mfma_f32_16x16x32_bf16 v[18:21], v[176:179], v[210:213], v[18:21]
	v_mfma_f32_16x16x32_bf16 v[6:9], v[168:171], v[218:221], v[6:9]
	v_mfma_f32_16x16x32_bf16 v[2:5], v[176:179], v[218:221], v[2:5]
	v_mfma_f32_16x16x32_bf16 v[54:57], v[172:175], v[198:201], v[54:57]
	v_mfma_f32_16x16x32_bf16 v[50:53], v[190:193], v[198:201], v[50:53]
	v_mfma_f32_16x16x32_bf16 v[38:41], v[172:175], v[206:209], v[38:41]
	v_mfma_f32_16x16x32_bf16 v[34:37], v[190:193], v[206:209], v[34:37]
	v_mfma_f32_16x16x32_bf16 v[22:25], v[172:175], v[214:217], v[22:25]
	v_mfma_f32_16x16x32_bf16 v[18:21], v[190:193], v[214:217], v[18:21]
	v_mfma_f32_16x16x32_bf16 v[6:9], v[172:175], v[222:225], v[6:9]
	v_mfma_f32_16x16x32_bf16 v[2:5], v[190:193], v[222:225], v[2:5]
	s_setprio 0
	s_barrier
	s_add_i32 s66, s66, 2
	s_add_u32 s61, s61, 0x100
	s_addc_u32 s62, s62, 0
	s_add_u32 s76, s76, 0x100
	s_addc_u32 s77, s77, 0
	s_cmp_gt_u32 s66, 29
	s_cbranch_scc0 .LBB0_78
	s_and_b64 vcc, exec, s[8:9]
	s_cbranch_vccz .LBB0_81
	s_barrier

; #define PG8_STAGE(bufoff, gbase, voff) do { _Pragma("unroll") for (int _i = 0; _i < 2; ++_i) \
;         __builtin_amdgcn_global_load_lds((const unsigned*)((const char*)(gbase) + (voff)[_i]), (PG8_LAS unsigned*)(lds + (bufoff) + ldsw + _i * 8192), 16, 0, 0); } while (0)
; #define PG8_LDA(dst, b, h) do { _Pragma("unroll") for (int m = 0; m < 4; ++m) _Pragma("unroll") for (int k = 0; k < 2; ++k) dst[m][k] = *(const PG8_LAS bf16x8*)(lds + PG8_SA(b, h) + aoff + m * 2048 + k * 1024); } while (0)
; #define PG8_LDB(dst, b, h) do { _Pragma("unroll") for (int n = 0; n < 2; ++n) _Pragma("unroll") for (int k = 0; k < 2; ++k) dst[n][k] = *(const PG8_LAS bf16x8*)(lds + PG8_SB(b, h) + boff + n * 2048 + k * 1024); } while (0)
; #define PG8_MMA(ai, bj, At, Bt) do { __builtin_amdgcn_s_setprio(1); _Pragma("unroll") for (int m = 0; m < 4; ++m) _Pragma("unroll") for (int n = 0; n < 2; ++n) _Pragma("unroll") for (int k = 0; k < 2; ++k) \
;         acc[ai][bj][m][n] = __builtin_amdgcn_mfma_f32_16x16x32_bf16(Bt[n][k], At[m][k], acc[ai][bj][m][n], 0, 0, 0); __builtin_amdgcn_s_setprio(0); } while (0)
; template <class Epi, class Sched, bool ALIGN_EPI = false, bool SP2 = false>
; __device__ __forceinline__ void gemm_phase(PG8_LAS unsigned char* lds, const Gemm g, const Sched& S, const Epi& E, const int wv) {
;     ...
;             if constexpr (SP2) {
;             PG8_LDB(B0, 0, 0); PG8_LDB(B1, 0, 1); PG8_SCHED; PG8_LDA(At, 0, 0); PG8_STAGE(PG8_SA(1, 1), a1 + hstep, voffA);
;             PG8_WAIT_V(8); PG8_WAIT_L(0); PG8_BAR; PG8_MMA(0, 0, At, B0); PG8_MMA(0, 1, At, B1); PG8_BAR; PG8_SCHED;
;             PG8_LDA(At, 0, 1); PG8_STAGE(PG8_SB(0, 0), b2, voffB); PG8_STAGE(PG8_SB(0, 1), b2 + hstep, voffB); PG8_STAGE(PG8_SA(0, 0), a2, voffA);
;             PG8_WAIT_V(8); PG8_WAIT_L(0); PG8_BAR; PG8_MMA(1, 0, At, B0); PG8_MMA(1, 1, At, B1); PG8_BAR; PG8_SCHED;
;             PG8_LDB(B0, 1, 0); PG8_LDB(B1, 1, 1); PG8_SCHED; PG8_LDA(At, 1, 0); PG8_STAGE(PG8_SA(0, 1), a2 + hstep, voffA);
;             PG8_WAIT_V(8); PG8_WAIT_L(0); PG8_BAR; PG8_MMA(0, 0, At, B0); PG8_MMA(0, 1, At, B1); PG8_BAR; PG8_SCHED;
;             PG8_LDA(At, 1, 1); PG8_STAGE(PG8_SB(1, 0), b3, voffB); PG8_STAGE(PG8_SB(1, 1), b3 + hstep, voffB); PG8_STAGE(PG8_SA(1, 0), a3, voffA);
;             PG8_WAIT_V(8); PG8_WAIT_L(0); PG8_BAR; PG8_MMA(1, 0, At, B0); PG8_MMA(1, 1, At, B1); PG8_BAR; PG8_SCHED;
.LBB0_151:
	s_add_u32 s62, s82, 0xfff80080
	s_addc_u32 s66, s83, -1
	s_add_i32 s68, 0, 0x10000
	s_cmp_eq_u32 s61, 28
	s_cselect_b32 s87, s34, s66
	s_cselect_b32 s86, s35, s62
	v_add_u32_e32 v146, s68, v154
	s_cselect_b32 s85, s47, s58
	s_cselect_b32 s84, s49, s57
	s_add_i32 s62, 0, 0x14000
	ds_read_b128 v[142:145], v146
	ds_read_b128 v[158:161], v146 offset:1024
	ds_read_b128 v[162:165], v146 offset:2048
	ds_read_b128 v[166:169], v146 offset:3072
	v_add_u32_e32 v146, s62, v154
	ds_read_b128 v[170:173], v146
	ds_read_b128 v[174:177], v146 offset:1024
	ds_read_b128 v[190:193], v146 offset:2048
	ds_read_b128 v[194:197], v146 offset:3072
	v_lshl_add_u64 v[146:147], s[82:83], 0, v[140:141]
	s_add_i32 m0, s8, 0xc000
	ds_read_b128 v[198:201], v156
	ds_read_b128 v[202:205], v156 offset:1024
	ds_read_b128 v[206:209], v156 offset:2048
	ds_read_b128 v[210:213], v156 offset:3072
	ds_read_b128 v[214:217], v156 offset:4096
	ds_read_b128 v[218:221], v156 offset:5120
	ds_read_b128 v[222:225], v156 offset:6144
	ds_read_b128 v[226:229], v156 offset:7168
	global_load_lds_dwordx4 v[146:147], off
	v_lshl_add_u64 v[146:147], s[82:83], 0, v[138:139]
	s_add_i32 m0, s8, 0xe000
	s_nop 0
	global_load_lds_dwordx4 v[146:147], off
	s_waitcnt vmcnt(8)
	s_waitcnt lgkmcnt(0)
	s_setprio 1
	s_barrier
	v_mfma_f32_16x16x32_bf16 v[126:129], v[142:145], v[198:201], v[126:129]
	v_mfma_f32_16x16x32_bf16 v[122:125], v[162:165], v[198:201], v[122:125]
	v_mfma_f32_16x16x32_bf16 v[110:113], v[142:145], v[206:209], v[110:113]
	v_mfma_f32_16x16x32_bf16 v[106:109], v[162:165], v[206:209], v[106:109]
	v_mfma_f32_16x16x32_bf16 v[94:97], v[142:145], v[214:217], v[94:97]
	v_mfma_f32_16x16x32_bf16 v[90:93], v[162:165], v[214:217], v[90:93]
	v_mfma_f32_16x16x32_bf16 v[78:81], v[142:145], v[222:225], v[78:81]
	v_mfma_f32_16x16x32_bf16 v[74:77], v[162:165], v[222:225], v[74:77]
	v_mfma_f32_16x16x32_bf16 v[126:129], v[158:161], v[202:205], v[126:129]
	v_mfma_f32_16x16x32_bf16 v[122:125], v[166:169], v[202:205], v[122:125]
	v_mfma_f32_16x16x32_bf16 v[110:113], v[158:161], v[210:213], v[110:113]
	v_mfma_f32_16x16x32_bf16 v[106:109], v[166:169], v[210:213], v[106:109]
	v_mfma_f32_16x16x32_bf16 v[94:97], v[158:161], v[218:221], v[94:97]
	v_mfma_f32_16x16x32_bf16 v[90:93], v[166:169], v[218:221], v[90:93]
	v_mfma_f32_16x16x32_bf16 v[78:81], v[158:161], v[226:229], v[78:81]
	v_mfma_f32_16x16x32_bf16 v[74:77], v[166:169], v[226:229], v[74:77]
	v_mfma_f32_16x16x32_bf16 v[118:121], v[170:173], v[198:201], v[118:121]
	v_mfma_f32_16x16x32_bf16 v[114:117], v[190:193], v[198:201], v[114:117]
	v_mfma_f32_16x16x32_bf16 v[102:105], v[170:173], v[206:209], v[102:105]
	v_mfma_f32_16x16x32_bf16 v[98:101], v[190:193], v[206:209], v[98:101]
	v_mfma_f32_16x16x32_bf16 v[86:89], v[170:173], v[214:217], v[86:89]
	v_mfma_f32_16x16x32_bf16 v[82:85], v[190:193], v[214:217], v[82:85]
	v_mfma_f32_16x16x32_bf16 v[70:73], v[170:173], v[222:225], v[70:73]
	v_mfma_f32_16x16x32_bf16 v[66:69], v[190:193], v[222:225], v[66:69]
	v_mfma_f32_16x16x32_bf16 v[118:121], v[174:177], v[202:205], v[118:121]
	v_mfma_f32_16x16x32_bf16 v[114:117], v[194:197], v[202:205], v[114:117]
	v_mfma_f32_16x16x32_bf16 v[102:105], v[174:177], v[210:213], v[102:105]
	v_mfma_f32_16x16x32_bf16 v[98:101], v[194:197], v[210:213], v[98:101]
	v_mfma_f32_16x16x32_bf16 v[86:89], v[174:177], v[218:221], v[86:89]
	v_mfma_f32_16x16x32_bf16 v[82:85], v[194:197], v[218:221], v[82:85]
	v_mfma_f32_16x16x32_bf16 v[70:73], v[174:177], v[226:229], v[70:73]
	v_mfma_f32_16x16x32_bf16 v[66:69], v[194:197], v[226:229], v[66:69]
	s_setprio 0
	s_barrier
	s_add_i32 s66, s68, s7
	v_lshl_add_u64 v[146:147], s[84:85], 0, v[134:135]
	s_mov_b32 m0, s66
	ds_read_b128 v[198:201], v156 offset:16384
	ds_read_b128 v[202:205], v156 offset:17408
	ds_read_b128 v[206:209], v156 offset:18432
	ds_read_b128 v[210:213], v156 offset:19456
	ds_read_b128 v[214:217], v156 offset:20480
	ds_read_b128 v[218:221], v156 offset:21504
	ds_read_b128 v[222:225], v156 offset:22528
	ds_read_b128 v[226:229], v156 offset:23552
	global_load_lds_dwordx4 v[146:147], off
	s_add_i32 m0, s66, 0x2000
	s_add_u32 s68, s84, 0x80000
	v_lshl_add_u64 v[148:149], s[84:85], 0, v[130:131]
	s_addc_u32 s69, s85, 0
	s_add_i32 s62, s62, s7
	global_load_lds_dwordx4 v[148:149], off
	v_lshl_add_u64 v[152:153], s[68:69], 0, v[134:135]
	s_mov_b32 m0, s62
	v_lshl_add_u64 v[178:179], s[86:87], 0, v[132:133]
	global_load_lds_dwordx4 v[152:153], off
	v_lshl_add_u64 v[152:153], s[68:69], 0, v[130:131]
	s_add_i32 m0, s62, 0x2000
	s_nop 0
	global_load_lds_dwordx4 v[152:153], off
	v_lshl_add_u64 v[152:153], s[86:87], 0, v[136:137]
	s_mov_b32 m0, s8
	s_nop 0
	global_load_lds_dwordx4 v[152:153], off
	s_mov_b32 m0, s9
	s_nop 0
	global_load_lds_dwordx4 v[178:179], off
	s_waitcnt vmcnt(8)
	s_waitcnt lgkmcnt(0)
	s_setprio 1
	s_barrier
; #define PG8_STAGE(bufoff, gbase, voff) do { _Pragma("unroll") for (int _i = 0; _i < 2; ++_i) \
;         __builtin_amdgcn_global_load_lds((const unsigned*)((const char*)(gbase) + (voff)[_i]), (PG8_LAS unsigned*)(lds + (bufoff) + ldsw + _i * 8192), 16, 0, 0); } while (0)
; #define PG8_LDA(dst, b, h) do { _Pragma("unroll") for (int m = 0; m < 4; ++m) _Pragma("unroll") for (int k = 0; k < 2; ++k) dst[m][k] = *(const PG8_LAS bf16x8*)(lds + PG8_SA(b, h) + aoff + m * 2048 + k * 1024); } while (0)
; #define PG8_LDB(dst, b, h) do { _Pragma("unroll") for (int n = 0; n < 2; ++n) _Pragma("unroll") for (int k = 0; k < 2; ++k) dst[n][k] = *(const PG8_LAS bf16x8*)(lds + PG8_SB(b, h) + boff + n * 2048 + k * 1024); } while (0)
; #define PG8_MMA(ai, bj, At, Bt) do { __builtin_amdgcn_s_setprio(1); _Pragma("unroll") for (int m = 0; m < 4; ++m) _Pragma("unroll") for (int n = 0; n < 2; ++n) _Pragma("unroll") for (int k = 0; k < 2; ++k) \
;         acc[ai][bj][m][n] = __builtin_amdgcn_mfma_f32_16x16x32_bf16(Bt[n][k], At[m][k], acc[ai][bj][m][n], 0, 0, 0); __builtin_amdgcn_s_setprio(0); } while (0)
; template <class Epi, class Sched, bool ALIGN_EPI = false, bool SP2 = false>
; __device__ __forceinline__ void gemm_phase(PG8_LAS unsigned char* lds, const Gemm g, const Sched& S, const Epi& E, const int wv) {
;     ...
;             if constexpr (SP2) {
;             PG8_LDB(B0, 0, 0); PG8_LDB(B1, 0, 1); PG8_SCHED; PG8_LDA(At, 0, 0); PG8_STAGE(PG8_SA(1, 1), a1 + hstep, voffA);
;             PG8_WAIT_V(8); PG8_WAIT_L(0); PG8_BAR; PG8_MMA(0, 0, At, B0); PG8_MMA(0, 1, At, B1); PG8_BAR; PG8_SCHED;
;             PG8_LDA(At, 0, 1); PG8_STAGE(PG8_SB(0, 0), b2, voffB); PG8_STAGE(PG8_SB(0, 1), b2 + hstep, voffB); PG8_STAGE(PG8_SA(0, 0), a2, voffA);
;             PG8_WAIT_V(8); PG8_WAIT_L(0); PG8_BAR; PG8_MMA(1, 0, At, B0); PG8_MMA(1, 1, At, B1); PG8_BAR; PG8_SCHED;
;             PG8_LDB(B0, 1, 0); PG8_LDB(B1, 1, 1); PG8_SCHED; PG8_LDA(At, 1, 0); PG8_STAGE(PG8_SA(0, 1), a2 + hstep, voffA);
;             PG8_WAIT_V(8); PG8_WAIT_L(0); PG8_BAR; PG8_MMA(0, 0, At, B0); PG8_MMA(0, 1, At, B1); PG8_BAR; PG8_SCHED;
;             PG8_LDA(At, 1, 1); PG8_STAGE(PG8_SB(1, 0), b3, voffB); PG8_STAGE(PG8_SB(1, 1), b3 + hstep, voffB); PG8_STAGE(PG8_SA(1, 0), a3, voffA);
;             PG8_WAIT_V(8); PG8_WAIT_L(0); PG8_BAR; PG8_MMA(1, 0, At, B0); PG8_MMA(1, 1, At, B1); PG8_BAR; PG8_SCHED;
	v_mfma_f32_16x16x32_bf16 v[62:65], v[142:145], v[198:201], v[62:65]
	v_mfma_f32_16x16x32_bf16 v[58:61], v[162:165], v[198:201], v[58:61]
	v_mfma_f32_16x16x32_bf16 v[46:49], v[142:145], v[206:209], v[46:49]
	v_mfma_f32_16x16x32_bf16 v[42:45], v[162:165], v[206:209], v[42:45]
	v_mfma_f32_16x16x32_bf16 v[30:33], v[142:145], v[214:217], v[30:33]
	v_mfma_f32_16x16x32_bf16 v[26:29], v[162:165], v[214:217], v[26:29]
	v_mfma_f32_16x16x32_bf16 v[14:17], v[142:145], v[222:225], v[14:17]
	v_mfma_f32_16x16x32_bf16 v[10:13], v[162:165], v[222:225], v[10:13]
	v_mfma_f32_16x16x32_bf16 v[62:65], v[158:161], v[202:205], v[62:65]
	v_mfma_f32_16x16x32_bf16 v[58:61], v[166:169], v[202:205], v[58:61]
	v_mfma_f32_16x16x32_bf16 v[46:49], v[158:161], v[210:213], v[46:49]
	v_mfma_f32_16x16x32_bf16 v[42:45], v[166:169], v[210:213], v[42:45]
	v_mfma_f32_16x16x32_bf16 v[30:33], v[158:161], v[218:221], v[30:33]
	v_mfma_f32_16x16x32_bf16 v[26:29], v[166:169], v[218:221], v[26:29]
	v_mfma_f32_16x16x32_bf16 v[14:17], v[158:161], v[226:229], v[14:17]
	v_mfma_f32_16x16x32_bf16 v[10:13], v[166:169], v[226:229], v[10:13]
	v_mfma_f32_16x16x32_bf16 v[54:57], v[170:173], v[198:201], v[54:57]
	v_mfma_f32_16x16x32_bf16 v[50:53], v[190:193], v[198:201], v[50:53]
	v_mfma_f32_16x16x32_bf16 v[38:41], v[170:173], v[206:209], v[38:41]
	v_mfma_f32_16x16x32_bf16 v[34:37], v[190:193], v[206:209], v[34:37]
	v_mfma_f32_16x16x32_bf16 v[22:25], v[170:173], v[214:217], v[22:25]
	v_mfma_f32_16x16x32_bf16 v[18:21], v[190:193], v[214:217], v[18:21]
	v_mfma_f32_16x16x32_bf16 v[6:9], v[170:173], v[222:225], v[6:9]
	v_mfma_f32_16x16x32_bf16 v[2:5], v[190:193], v[222:225], v[2:5]
	v_mfma_f32_16x16x32_bf16 v[54:57], v[174:177], v[202:205], v[54:57]
	v_mfma_f32_16x16x32_bf16 v[50:53], v[194:197], v[202:205], v[50:53]
	v_mfma_f32_16x16x32_bf16 v[38:41], v[174:177], v[210:213], v[38:41]
	v_mfma_f32_16x16x32_bf16 v[34:37], v[194:197], v[210:213], v[34:37]
	v_mfma_f32_16x16x32_bf16 v[22:25], v[174:177], v[218:221], v[22:25]
	v_mfma_f32_16x16x32_bf16 v[18:21], v[194:197], v[218:221], v[18:21]
	v_mfma_f32_16x16x32_bf16 v[6:9], v[174:177], v[226:229], v[6:9]
	v_mfma_f32_16x16x32_bf16 v[2:5], v[194:197], v[226:229], v[2:5]
	s_setprio 0
	s_barrier
	s_add_i32 s62, 0, 0x18000
	v_add_u32_e32 v157, s62, v154
	s_add_i32 s66, 0, 0x1c000
	ds_read_b128 v[142:145], v157
	ds_read_b128 v[158:161], v157 offset:1024
	ds_read_b128 v[162:165], v157 offset:2048
	ds_read_b128 v[166:169], v157 offset:3072
	v_add_u32_e32 v157, s66, v154
	ds_read_b128 v[170:173], v157
	ds_read_b128 v[174:177], v157 offset:1024
	ds_read_b128 v[190:193], v157 offset:2048
	ds_read_b128 v[194:197], v157 offset:3072
	s_add_u32 s68, s86, 0x80000
	s_addc_u32 s69, s87, 0
	s_mov_b32 m0, s14
	v_lshl_add_u64 v[230:231], s[68:69], 0, v[136:137]
	ds_read_b128 v[198:201], v156 offset:32768
	ds_read_b128 v[202:205], v156 offset:33792
	ds_read_b128 v[206:209], v156 offset:34816
	ds_read_b128 v[210:213], v156 offset:35840
	ds_read_b128 v[214:217], v156 offset:36864
	ds_read_b128 v[218:221], v156 offset:37888
	ds_read_b128 v[222:225], v156 offset:38912
	ds_read_b128 v[226:229], v156 offset:39936
	global_load_lds_dwordx4 v[230:231], off
	v_lshl_add_u64 v[230:231], s[68:69], 0, v[132:133]
	s_mov_b32 m0, s15
	s_nop 0
	global_load_lds_dwordx4 v[230:231], off
	s_waitcnt vmcnt(8)
	s_waitcnt lgkmcnt(0)
	s_setprio 1
	s_barrier
	v_mfma_f32_16x16x32_bf16 v[126:129], v[142:145], v[198:201], v[126:129]
	v_mfma_f32_16x16x32_bf16 v[122:125], v[162:165], v[198:201], v[122:125]
	v_mfma_f32_16x16x32_bf16 v[110:113], v[142:145], v[206:209], v[110:113]
	v_mfma_f32_16x16x32_bf16 v[106:109], v[162:165], v[206:209], v[106:109]
	v_mfma_f32_16x16x32_bf16 v[94:97], v[142:145], v[214:217], v[94:97]
	v_mfma_f32_16x16x32_bf16 v[90:93], v[162:165], v[214:217], v[90:93]
	v_mfma_f32_16x16x32_bf16 v[78:81], v[142:145], v[222:225], v[78:81]
	v_mfma_f32_16x16x32_bf16 v[74:77], v[162:165], v[222:225], v[74:77]
	v_mfma_f32_16x16x32_bf16 v[126:129], v[158:161], v[202:205], v[126:129]
	v_mfma_f32_16x16x32_bf16 v[122:125], v[166:169], v[202:205], v[122:125]
	v_mfma_f32_16x16x32_bf16 v[110:113], v[158:161], v[210:213], v[110:113]
	v_mfma_f32_16x16x32_bf16 v[106:109], v[166:169], v[210:213], v[106:109]
	v_mfma_f32_16x16x32_bf16 v[94:97], v[158:161], v[218:221], v[94:97]
	v_mfma_f32_16x16x32_bf16 v[90:93], v[166:169], v[218:221], v[90:93]
	v_mfma_f32_16x16x32_bf16 v[78:81], v[158:161], v[226:229], v[78:81]
	v_mfma_f32_16x16x32_bf16 v[74:77], v[166:169], v[226:229], v[74:77]
	v_mfma_f32_16x16x32_bf16 v[118:121], v[170:173], v[198:201], v[118:121]
	v_mfma_f32_16x16x32_bf16 v[114:117], v[190:193], v[198:201], v[114:117]
	v_mfma_f32_16x16x32_bf16 v[102:105], v[170:173], v[206:209], v[102:105]
	v_mfma_f32_16x16x32_bf16 v[98:101], v[190:193], v[206:209], v[98:101]
	v_mfma_f32_16x16x32_bf16 v[86:89], v[170:173], v[214:217], v[86:89]
	v_mfma_f32_16x16x32_bf16 v[82:85], v[190:193], v[214:217], v[82:85]
	v_mfma_f32_16x16x32_bf16 v[70:73], v[170:173], v[222:225], v[70:73]
	v_mfma_f32_16x16x32_bf16 v[66:69], v[190:193], v[222:225], v[66:69]
	v_mfma_f32_16x16x32_bf16 v[118:121], v[174:177], v[202:205], v[118:121]
	v_mfma_f32_16x16x32_bf16 v[114:117], v[194:197], v[202:205], v[114:117]
	v_mfma_f32_16x16x32_bf16 v[102:105], v[174:177], v[210:213], v[102:105]
	v_mfma_f32_16x16x32_bf16 v[98:101], v[194:197], v[210:213], v[98:101]
	v_mfma_f32_16x16x32_bf16 v[86:89], v[174:177], v[218:221], v[86:89]
	v_mfma_f32_16x16x32_bf16 v[82:85], v[194:197], v[218:221], v[82:85]
	v_mfma_f32_16x16x32_bf16 v[70:73], v[174:177], v[226:229], v[70:73]
	v_mfma_f32_16x16x32_bf16 v[66:69], v[194:197], v[226:229], v[66:69]
	s_setprio 0
	s_barrier
; #define PG8_STAGE(bufoff, gbase, voff) do { _Pragma("unroll") for (int _i = 0; _i < 2; ++_i) \
;         __builtin_amdgcn_global_load_lds((const unsigned*)((const char*)(gbase) + (voff)[_i]), (PG8_LAS unsigned*)(lds + (bufoff) + ldsw + _i * 8192), 16, 0, 0); } while (0)
; #define PG8_LDA(dst, b, h) do { _Pragma("unroll") for (int m = 0; m < 4; ++m) _Pragma("unroll") for (int k = 0; k < 2; ++k) dst[m][k] = *(const PG8_LAS bf16x8*)(lds + PG8_SA(b, h) + aoff + m * 2048 + k * 1024); } while (0)
; #define PG8_LDB(dst, b, h) do { _Pragma("unroll") for (int n = 0; n < 2; ++n) _Pragma("unroll") for (int k = 0; k < 2; ++k) dst[n][k] = *(const PG8_LAS bf16x8*)(lds + PG8_SB(b, h) + boff + n * 2048 + k * 1024); } while (0)
; #define PG8_MMA(ai, bj, At, Bt) do { __builtin_amdgcn_s_setprio(1); _Pragma("unroll") for (int m = 0; m < 4; ++m) _Pragma("unroll") for (int n = 0; n < 2; ++n) _Pragma("unroll") for (int k = 0; k < 2; ++k) \
;         acc[ai][bj][m][n] = __builtin_amdgcn_mfma_f32_16x16x32_bf16(Bt[n][k], At[m][k], acc[ai][bj][m][n], 0, 0, 0); __builtin_amdgcn_s_setprio(0); } while (0)
; template <class Epi, class Sched, bool ALIGN_EPI = false, bool SP2 = false>
; __device__ __forceinline__ void gemm_phase(PG8_LAS unsigned char* lds, const Gemm g, const Sched& S, const Epi& E, const int wv) {
;     ...
;             if constexpr (SP2) {
;             PG8_LDB(B0, 0, 0); PG8_LDB(B1, 0, 1); PG8_SCHED; PG8_LDA(At, 0, 0); PG8_STAGE(PG8_SA(1, 1), a1 + hstep, voffA);
;             PG8_WAIT_V(8); PG8_WAIT_L(0); PG8_BAR; PG8_MMA(0, 0, At, B0); PG8_MMA(0, 1, At, B1); PG8_BAR; PG8_SCHED;
;             PG8_LDA(At, 0, 1); PG8_STAGE(PG8_SB(0, 0), b2, voffB); PG8_STAGE(PG8_SB(0, 1), b2 + hstep, voffB); PG8_STAGE(PG8_SA(0, 0), a2, voffA);
;             PG8_WAIT_V(8); PG8_WAIT_L(0); PG8_BAR; PG8_MMA(1, 0, At, B0); PG8_MMA(1, 1, At, B1); PG8_BAR; PG8_SCHED;
;             PG8_LDB(B0, 1, 0); PG8_LDB(B1, 1, 1); PG8_SCHED; PG8_LDA(At, 1, 0); PG8_STAGE(PG8_SA(0, 1), a2 + hstep, voffA);
;             PG8_WAIT_V(8); PG8_WAIT_L(0); PG8_BAR; PG8_MMA(0, 0, At, B0); PG8_MMA(0, 1, At, B1); PG8_BAR; PG8_SCHED;
;             PG8_LDA(At, 1, 1); PG8_STAGE(PG8_SB(1, 0), b3, voffB); PG8_STAGE(PG8_SB(1, 1), b3 + hstep, voffB); PG8_STAGE(PG8_SA(1, 0), a3, voffA);
;             PG8_WAIT_V(8); PG8_WAIT_L(0); PG8_BAR; PG8_MMA(1, 0, At, B0); PG8_MMA(1, 1, At, B1); PG8_BAR; PG8_SCHED;
	s_add_i32 s62, s62, s7
	v_lshl_add_u64 v[146:147], v[146:147], 0, s[26:27]
	s_mov_b32 m0, s62
	ds_read_b128 v[198:201], v156 offset:49152
	ds_read_b128 v[202:205], v156 offset:50176
	ds_read_b128 v[206:209], v156 offset:51200
	ds_read_b128 v[210:213], v156 offset:52224
	ds_read_b128 v[214:217], v156 offset:53248
	ds_read_b128 v[218:221], v156 offset:54272
	ds_read_b128 v[222:225], v156 offset:55296
	ds_read_b128 v[226:229], v156 offset:56320
	global_load_lds_dwordx4 v[146:147], off
	s_add_i32 m0, s62, 0x2000
	s_add_u32 s68, s84, 0x80080
	v_lshl_add_u64 v[146:147], v[148:149], 0, s[26:27]
	s_addc_u32 s69, s85, 0
	s_add_i32 s62, s66, s7
	global_load_lds_dwordx4 v[146:147], off
	v_lshl_add_u64 v[146:147], s[68:69], 0, v[134:135]
	s_mov_b32 m0, s62
	s_nop 0
	global_load_lds_dwordx4 v[146:147], off
	v_lshl_add_u64 v[146:147], s[68:69], 0, v[130:131]
	s_add_i32 m0, s62, 0x2000
	s_nop 0
	global_load_lds_dwordx4 v[146:147], off
	v_lshl_add_u64 v[146:147], v[152:153], 0, s[26:27]
	s_mov_b32 m0, s16
	s_nop 0
	global_load_lds_dwordx4 v[146:147], off
	v_lshl_add_u64 v[146:147], v[178:179], 0, s[26:27]
	s_mov_b32 m0, s17
	s_nop 0
	global_load_lds_dwordx4 v[146:147], off
	s_waitcnt vmcnt(8)
	s_waitcnt lgkmcnt(0)
	s_setprio 1
	s_barrier
	v_mfma_f32_16x16x32_bf16 v[62:65], v[142:145], v[198:201], v[62:65]
	v_mfma_f32_16x16x32_bf16 v[58:61], v[162:165], v[198:201], v[58:61]
	v_mfma_f32_16x16x32_bf16 v[46:49], v[142:145], v[206:209], v[46:49]
	v_mfma_f32_16x16x32_bf16 v[42:45], v[162:165], v[206:209], v[42:45]
	v_mfma_f32_16x16x32_bf16 v[30:33], v[142:145], v[214:217], v[30:33]
	v_mfma_f32_16x16x32_bf16 v[26:29], v[162:165], v[214:217], v[26:29]
	v_mfma_f32_16x16x32_bf16 v[14:17], v[142:145], v[222:225], v[14:17]
	v_mfma_f32_16x16x32_bf16 v[10:13], v[162:165], v[222:225], v[10:13]
	v_mfma_f32_16x16x32_bf16 v[62:65], v[158:161], v[202:205], v[62:65]
	v_mfma_f32_16x16x32_bf16 v[58:61], v[166:169], v[202:205], v[58:61]
	v_mfma_f32_16x16x32_bf16 v[46:49], v[158:161], v[210:213], v[46:49]
	v_mfma_f32_16x16x32_bf16 v[42:45], v[166:169], v[210:213], v[42:45]
	v_mfma_f32_16x16x32_bf16 v[30:33], v[158:161], v[218:221], v[30:33]
	v_mfma_f32_16x16x32_bf16 v[26:29], v[166:169], v[218:221], v[26:29]
	v_mfma_f32_16x16x32_bf16 v[14:17], v[158:161], v[226:229], v[14:17]
	v_mfma_f32_16x16x32_bf16 v[10:13], v[166:169], v[226:229], v[10:13]
	v_mfma_f32_16x16x32_bf16 v[54:57], v[170:173], v[198:201], v[54:57]
	v_mfma_f32_16x16x32_bf16 v[50:53], v[190:193], v[198:201], v[50:53]
	v_mfma_f32_16x16x32_bf16 v[38:41], v[170:173], v[206:209], v[38:41]
	v_mfma_f32_16x16x32_bf16 v[34:37], v[190:193], v[206:209], v[34:37]
	v_mfma_f32_16x16x32_bf16 v[22:25], v[170:173], v[214:217], v[22:25]
	v_mfma_f32_16x16x32_bf16 v[18:21], v[190:193], v[214:217], v[18:21]
	v_mfma_f32_16x16x32_bf16 v[6:9], v[170:173], v[222:225], v[6:9]
	v_mfma_f32_16x16x32_bf16 v[2:5], v[190:193], v[222:225], v[2:5]
	v_mfma_f32_16x16x32_bf16 v[54:57], v[174:177], v[202:205], v[54:57]
	v_mfma_f32_16x16x32_bf16 v[50:53], v[194:197], v[202:205], v[50:53]
	v_mfma_f32_16x16x32_bf16 v[38:41], v[174:177], v[210:213], v[38:41]
	v_mfma_f32_16x16x32_bf16 v[34:37], v[194:197], v[210:213], v[34:37]
	v_mfma_f32_16x16x32_bf16 v[22:25], v[174:177], v[218:221], v[22:25]
	v_mfma_f32_16x16x32_bf16 v[18:21], v[194:197], v[218:221], v[18:21]
	v_mfma_f32_16x16x32_bf16 v[6:9], v[174:177], v[226:229], v[6:9]
	v_mfma_f32_16x16x32_bf16 v[2:5], v[194:197], v[226:229], v[2:5]
	s_setprio 0
	s_barrier
	s_add_i32 s61, s61, 2
	s_add_u32 s57, s57, 0x100
	s_addc_u32 s58, s58, 0
	s_add_u32 s82, s82, 0x100
	s_addc_u32 s83, s83, 0
	s_cmp_gt_u32 s61, 29
	s_cbranch_scc0 .LBB0_151
	s_and_b64 vcc, exec, s[44:45]
	s_movk_i32 s57, 0x3df
	s_cbranch_vccz .LBB0_154
	s_barrier

; #define PG8_STAGE(bufoff, gbase, voff) do { _Pragma("unroll") for (int _i = 0; _i < 2; ++_i) \
;         __builtin_amdgcn_global_load_lds((const unsigned*)((const char*)(gbase) + (voff)[_i]), (PG8_LAS unsigned*)(lds + (bufoff) + ldsw + _i * 8192), 16, 0, 0); } while (0)
; #define PG8_LDA(dst, b, h) do { _Pragma("unroll") for (int m = 0; m < 4; ++m) _Pragma("unroll") for (int k = 0; k < 2; ++k) dst[m][k] = *(const PG8_LAS bf16x8*)(lds + PG8_SA(b, h) + aoff + m * 2048 + k * 1024); } while (0)
; #define PG8_LDB(dst, b, h) do { _Pragma("unroll") for (int n = 0; n < 2; ++n) _Pragma("unroll") for (int k = 0; k < 2; ++k) dst[n][k] = *(const PG8_LAS bf16x8*)(lds + PG8_SB(b, h) + boff + n * 2048 + k * 1024); } while (0)
; #define PG8_MMA(ai, bj, At, Bt) do { __builtin_amdgcn_s_setprio(1); _Pragma("unroll") for (int m = 0; m < 4; ++m) _Pragma("unroll") for (int n = 0; n < 2; ++n) _Pragma("unroll") for (int k = 0; k < 2; ++k) \
;         acc[ai][bj][m][n] = __builtin_amdgcn_mfma_f32_16x16x32_bf16(Bt[n][k], At[m][k], acc[ai][bj][m][n], 0, 0, 0); __builtin_amdgcn_s_setprio(0); } while (0)
; template <class Epi, class Sched, bool ALIGN_EPI = false, bool SP2 = false>
; __device__ __forceinline__ void gemm_phase(PG8_LAS unsigned char* lds, const Gemm g, const Sched& S, const Epi& E, const int wv) {
;     ...
;             if constexpr (SP2) {
;             PG8_LDB(B0, 0, 0); PG8_LDB(B1, 0, 1); PG8_SCHED; PG8_LDA(At, 0, 0); PG8_STAGE(PG8_SA(1, 1), a1 + hstep, voffA);
;             PG8_WAIT_V(8); PG8_WAIT_L(0); PG8_BAR; PG8_MMA(0, 0, At, B0); PG8_MMA(0, 1, At, B1); PG8_BAR; PG8_SCHED;
;             PG8_LDA(At, 0, 1); PG8_STAGE(PG8_SB(0, 0), b2, voffB); PG8_STAGE(PG8_SB(0, 1), b2 + hstep, voffB); PG8_STAGE(PG8_SA(0, 0), a2, voffA);
;             PG8_WAIT_V(8); PG8_WAIT_L(0); PG8_BAR; PG8_MMA(1, 0, At, B0); PG8_MMA(1, 1, At, B1); PG8_BAR; PG8_SCHED;
;             PG8_LDB(B0, 1, 0); PG8_LDB(B1, 1, 1); PG8_SCHED; PG8_LDA(At, 1, 0); PG8_STAGE(PG8_SA(0, 1), a2 + hstep, voffA);
;             PG8_WAIT_V(8); PG8_WAIT_L(0); PG8_BAR; PG8_MMA(0, 0, At, B0); PG8_MMA(0, 1, At, B1); PG8_BAR; PG8_SCHED;
;             PG8_LDA(At, 1, 1); PG8_STAGE(PG8_SB(1, 0), b3, voffB); PG8_STAGE(PG8_SB(1, 1), b3 + hstep, voffB); PG8_STAGE(PG8_SA(1, 0), a3, voffA);
;             PG8_WAIT_V(8); PG8_WAIT_L(0); PG8_BAR; PG8_MMA(1, 0, At, B0); PG8_MMA(1, 1, At, B1); PG8_BAR; PG8_SCHED;
.LBB0_169:
	s_add_u32 s35, s9, s74
	s_addc_u32 s41, s14, s75
	s_and_b64 s[0:1], s[0:1], exec
	s_cselect_b32 s1, s41, s85
	s_cselect_b32 s0, s35, s84
	s_add_i32 s35, 0, 0x10000
	s_add_i32 s41, 0, 0x14000
	v_add_u32_e32 v14, s35, v0
	v_add_u32_e32 v30, s41, v0
	ds_read_b128 v[2:5], v14
	ds_read_b128 v[6:9], v14 offset:1024
	ds_read_b128 v[10:13], v14 offset:2048
	ds_read_b128 v[14:17], v14 offset:3072
	ds_read_b128 v[18:21], v30
	ds_read_b128 v[22:25], v30 offset:1024
	ds_read_b128 v[26:29], v30 offset:2048
	ds_read_b128 v[30:33], v30 offset:3072
	s_add_u32 s68, s84, 0x80080
	s_addc_u32 s69, s85, 0
	v_lshl_add_u64 v[78:79], s[68:69], 0, v[72:73]
	s_add_i32 m0, s8, 0xc000
	ds_read_b128 v[34:37], v77
	ds_read_b128 v[38:41], v77 offset:1024
	ds_read_b128 v[42:45], v77 offset:2048
	ds_read_b128 v[46:49], v77 offset:3072
	ds_read_b128 v[50:53], v77 offset:4096
	ds_read_b128 v[54:57], v77 offset:5120
	ds_read_b128 v[58:61], v77 offset:6144
	ds_read_b128 v[62:65], v77 offset:7168
	global_load_lds_dwordx4 v[78:79], off
	v_lshl_add_u64 v[78:79], s[68:69], 0, v[68:69]
	s_add_i32 m0, s8, 0xe000
	s_nop 0
	global_load_lds_dwordx4 v[78:79], off
	s_waitcnt vmcnt(8)
	s_waitcnt lgkmcnt(0)
	s_setprio 1
	s_barrier
	v_mfma_f32_16x16x32_bf16 v[78:81], v[2:5], v[34:37], 0
	v_mfma_f32_16x16x32_bf16 v[86:89], v[2:5], v[42:45], 0
	v_mfma_f32_16x16x32_bf16 v[94:97], v[2:5], v[50:53], 0
	v_mfma_f32_16x16x32_bf16 v[2:5], v[2:5], v[58:61], 0
	v_mfma_f32_16x16x32_bf16 v[78:81], v[6:9], v[38:41], v[78:81]
	v_mfma_f32_16x16x32_bf16 v[86:89], v[6:9], v[46:49], v[86:89]
	v_mfma_f32_16x16x32_bf16 v[94:97], v[6:9], v[54:57], v[94:97]
	v_mfma_f32_16x16x32_bf16 v[2:5], v[6:9], v[62:65], v[2:5]
	v_mfma_f32_16x16x32_bf16 v[6:9], v[10:13], v[58:61], 0
	v_mfma_f32_16x16x32_bf16 v[82:85], v[10:13], v[34:37], 0
	v_mfma_f32_16x16x32_bf16 v[90:93], v[10:13], v[42:45], 0
	v_mfma_f32_16x16x32_bf16 v[98:101], v[10:13], v[50:53], 0
	v_mfma_f32_16x16x32_bf16 v[6:9], v[14:17], v[62:65], v[6:9]
	v_mfma_f32_16x16x32_bf16 v[82:85], v[14:17], v[38:41], v[82:85]
	v_mfma_f32_16x16x32_bf16 v[90:93], v[14:17], v[46:49], v[90:93]
	v_mfma_f32_16x16x32_bf16 v[98:101], v[14:17], v[54:57], v[98:101]
	v_mfma_f32_16x16x32_bf16 v[10:13], v[18:21], v[34:37], 0
	v_mfma_f32_16x16x32_bf16 v[102:105], v[22:25], v[38:41], v[10:13]
	v_mfma_f32_16x16x32_bf16 v[10:13], v[26:29], v[34:37], 0
	v_mfma_f32_16x16x32_bf16 v[106:109], v[30:33], v[38:41], v[10:13]
	v_mfma_f32_16x16x32_bf16 v[10:13], v[18:21], v[42:45], 0
	v_mfma_f32_16x16x32_bf16 v[110:113], v[22:25], v[46:49], v[10:13]
	v_mfma_f32_16x16x32_bf16 v[10:13], v[26:29], v[42:45], 0
	v_mfma_f32_16x16x32_bf16 v[42:45], v[30:33], v[46:49], v[10:13]
	v_mfma_f32_16x16x32_bf16 v[10:13], v[18:21], v[50:53], 0
	v_mfma_f32_16x16x32_bf16 v[46:49], v[22:25], v[54:57], v[10:13]
	v_mfma_f32_16x16x32_bf16 v[10:13], v[26:29], v[50:53], 0
	v_mfma_f32_16x16x32_bf16 v[114:117], v[30:33], v[54:57], v[10:13]
	v_mfma_f32_16x16x32_bf16 v[10:13], v[18:21], v[58:61], 0
	v_mfma_f32_16x16x32_bf16 v[118:121], v[22:25], v[62:65], v[10:13]
	v_mfma_f32_16x16x32_bf16 v[10:13], v[26:29], v[58:61], 0
	v_mfma_f32_16x16x32_bf16 v[30:33], v[30:33], v[62:65], v[10:13]
	s_setprio 0
	s_barrier
	s_add_i32 s35, s35, s7
	v_lshl_add_u64 v[146:147], s[44:45], 0, v[70:71]
	s_mov_b32 m0, s35
	v_lshl_add_u64 v[148:149], s[44:45], 0, v[66:67]
	global_load_lds_dwordx4 v[146:147], off
	s_add_i32 m0, s35, 0x2000
	s_add_u32 s68, s44, 0x80000
	s_addc_u32 s69, s45, 0
	s_add_i32 s35, s41, s7
	global_load_lds_dwordx4 v[148:149], off
	v_lshl_add_u64 v[10:11], s[68:69], 0, v[70:71]
	s_mov_b32 m0, s35
	v_lshl_add_u64 v[172:173], s[0:1], 0, v[72:73]
	global_load_lds_dwordx4 v[10:11], off
	v_lshl_add_u64 v[10:11], s[68:69], 0, v[66:67]
	s_add_i32 m0, s35, 0x2000
	v_lshl_add_u64 v[174:175], s[0:1], 0, v[68:69]
	global_load_lds_dwordx4 v[10:11], off
	s_mov_b32 m0, s8
	s_nop 0
	global_load_lds_dwordx4 v[172:173], off
	s_mov_b32 m0, s15
	s_nop 0
	global_load_lds_dwordx4 v[174:175], off
	s_waitcnt vmcnt(8)
	s_waitcnt lgkmcnt(0)
	s_barrier
	s_setprio 1
	s_setprio 0
	s_setprio 1
	s_setprio 0
	s_barrier
; #define PG8_STAGE(bufoff, gbase, voff) do { _Pragma("unroll") for (int _i = 0; _i < 2; ++_i) \
;         __builtin_amdgcn_global_load_lds((const unsigned*)((const char*)(gbase) + (voff)[_i]), (PG8_LAS unsigned*)(lds + (bufoff) + ldsw + _i * 8192), 16, 0, 0); } while (0)
; #define PG8_LDA(dst, b, h) do { _Pragma("unroll") for (int m = 0; m < 4; ++m) _Pragma("unroll") for (int k = 0; k < 2; ++k) dst[m][k] = *(const PG8_LAS bf16x8*)(lds + PG8_SA(b, h) + aoff + m * 2048 + k * 1024); } while (0)
; #define PG8_LDB(dst, b, h) do { _Pragma("unroll") for (int n = 0; n < 2; ++n) _Pragma("unroll") for (int k = 0; k < 2; ++k) dst[n][k] = *(const PG8_LAS bf16x8*)(lds + PG8_SB(b, h) + boff + n * 2048 + k * 1024); } while (0)
; #define PG8_MMA(ai, bj, At, Bt) do { __builtin_amdgcn_s_setprio(1); _Pragma("unroll") for (int m = 0; m < 4; ++m) _Pragma("unroll") for (int n = 0; n < 2; ++n) _Pragma("unroll") for (int k = 0; k < 2; ++k) \
;         acc[ai][bj][m][n] = __builtin_amdgcn_mfma_f32_16x16x32_bf16(Bt[n][k], At[m][k], acc[ai][bj][m][n], 0, 0, 0); __builtin_amdgcn_s_setprio(0); } while (0)
; template <class Epi, class Sched, bool ALIGN_EPI = false, bool SP2 = false>
; __device__ __forceinline__ void gemm_phase(PG8_LAS unsigned char* lds, const Gemm g, const Sched& S, const Epi& E, const int wv) {
;     ...
;             if constexpr (SP2) {
;             PG8_LDB(B0, 0, 0); PG8_LDB(B1, 0, 1); PG8_SCHED; PG8_LDA(At, 0, 0); PG8_STAGE(PG8_SA(1, 1), a1 + hstep, voffA);
;             PG8_WAIT_V(8); PG8_WAIT_L(0); PG8_BAR; PG8_MMA(0, 0, At, B0); PG8_MMA(0, 1, At, B1); PG8_BAR; PG8_SCHED;
;             PG8_LDA(At, 0, 1); PG8_STAGE(PG8_SB(0, 0), b2, voffB); PG8_STAGE(PG8_SB(0, 1), b2 + hstep, voffB); PG8_STAGE(PG8_SA(0, 0), a2, voffA);
;             PG8_WAIT_V(8); PG8_WAIT_L(0); PG8_BAR; PG8_MMA(1, 0, At, B0); PG8_MMA(1, 1, At, B1); PG8_BAR; PG8_SCHED;
;             PG8_LDB(B0, 1, 0); PG8_LDB(B1, 1, 1); PG8_SCHED; PG8_LDA(At, 1, 0); PG8_STAGE(PG8_SA(0, 1), a2 + hstep, voffA);
;             PG8_WAIT_V(8); PG8_WAIT_L(0); PG8_BAR; PG8_MMA(0, 0, At, B0); PG8_MMA(0, 1, At, B1); PG8_BAR; PG8_SCHED;
;             PG8_LDA(At, 1, 1); PG8_STAGE(PG8_SB(1, 0), b3, voffB); PG8_STAGE(PG8_SB(1, 1), b3 + hstep, voffB); PG8_STAGE(PG8_SA(1, 0), a3, voffA);
;             PG8_WAIT_V(8); PG8_WAIT_L(0); PG8_BAR; PG8_MMA(1, 0, At, B0); PG8_MMA(1, 1, At, B1); PG8_BAR; PG8_SCHED;
	s_add_i32 s35, 0, 0x18000
	v_add_u32_e32 v10, s35, v0
	s_add_i32 s41, 0, 0x1c000
	ds_read_b128 v[26:29], v10
	ds_read_b128 v[50:53], v10 offset:1024
	ds_read_b128 v[54:57], v10 offset:2048
	ds_read_b128 v[58:61], v10 offset:3072
	v_add_u32_e32 v10, s41, v0
	ds_read_b128 v[122:125], v10
	ds_read_b128 v[126:129], v10 offset:1024
	ds_read_b128 v[130:133], v10 offset:2048
	ds_read_b128 v[134:137], v10 offset:3072
	s_add_u32 s68, s0, 0x80000
	s_addc_u32 s69, s1, 0
	s_mov_b32 m0, s16
	v_lshl_add_u64 v[10:11], s[68:69], 0, v[72:73]
	ds_read_b128 v[62:65], v77 offset:32768
	ds_read_b128 v[138:141], v77 offset:33792
	ds_read_b128 v[142:145], v77 offset:34816
	ds_read_b128 v[152:155], v77 offset:35840
	ds_read_b128 v[156:159], v77 offset:36864
	ds_read_b128 v[160:163], v77 offset:37888
	ds_read_b128 v[164:167], v77 offset:38912
	ds_read_b128 v[168:171], v77 offset:39936
	global_load_lds_dwordx4 v[10:11], off
	v_lshl_add_u64 v[10:11], s[68:69], 0, v[68:69]
	s_mov_b32 m0, s17
	s_nop 0
	global_load_lds_dwordx4 v[10:11], off
	s_waitcnt vmcnt(8)
	s_waitcnt lgkmcnt(0)
	s_setprio 1
	s_barrier
	v_mfma_f32_16x16x32_bf16 v[10:13], v[26:29], v[62:65], v[78:81]
	v_mfma_f32_16x16x32_bf16 v[34:37], v[50:53], v[138:141], v[10:13]
	v_mfma_f32_16x16x32_bf16 v[10:13], v[54:57], v[62:65], v[82:85]
	v_mfma_f32_16x16x32_bf16 v[38:41], v[58:61], v[138:141], v[10:13]
	v_mfma_f32_16x16x32_bf16 v[10:13], v[26:29], v[142:145], v[86:89]
	v_mfma_f32_16x16x32_bf16 v[18:21], v[50:53], v[152:155], v[10:13]
	v_mfma_f32_16x16x32_bf16 v[10:13], v[54:57], v[142:145], v[90:93]
	v_mfma_f32_16x16x32_bf16 v[22:25], v[58:61], v[152:155], v[10:13]
	v_mfma_f32_16x16x32_bf16 v[10:13], v[26:29], v[156:159], v[94:97]
	v_mfma_f32_16x16x32_bf16 v[14:17], v[54:57], v[156:159], v[98:101]
	v_mfma_f32_16x16x32_bf16 v[2:5], v[26:29], v[164:167], v[2:5]
	v_mfma_f32_16x16x32_bf16 v[6:9], v[54:57], v[164:167], v[6:9]
	v_mfma_f32_16x16x32_bf16 v[10:13], v[50:53], v[160:163], v[10:13]
	v_mfma_f32_16x16x32_bf16 v[14:17], v[58:61], v[160:163], v[14:17]
	v_mfma_f32_16x16x32_bf16 v[2:5], v[50:53], v[168:171], v[2:5]
	v_mfma_f32_16x16x32_bf16 v[6:9], v[58:61], v[168:171], v[6:9]
	v_mfma_f32_16x16x32_bf16 v[26:29], v[122:125], v[62:65], v[102:105]
	v_mfma_f32_16x16x32_bf16 v[58:61], v[126:129], v[138:141], v[26:29]
	v_mfma_f32_16x16x32_bf16 v[26:29], v[130:133], v[62:65], v[106:109]
	v_mfma_f32_16x16x32_bf16 v[62:65], v[134:137], v[138:141], v[26:29]
	v_mfma_f32_16x16x32_bf16 v[26:29], v[122:125], v[142:145], v[110:113]
	v_mfma_f32_16x16x32_bf16 v[50:53], v[126:129], v[152:155], v[26:29]
	v_mfma_f32_16x16x32_bf16 v[26:29], v[130:133], v[142:145], v[42:45]
	v_mfma_f32_16x16x32_bf16 v[54:57], v[134:137], v[152:155], v[26:29]
	v_mfma_f32_16x16x32_bf16 v[26:29], v[122:125], v[156:159], v[46:49]
	v_mfma_f32_16x16x32_bf16 v[42:45], v[126:129], v[160:163], v[26:29]
	v_mfma_f32_16x16x32_bf16 v[26:29], v[130:133], v[156:159], v[114:117]
	v_mfma_f32_16x16x32_bf16 v[46:49], v[134:137], v[160:163], v[26:29]
	v_mfma_f32_16x16x32_bf16 v[26:29], v[122:125], v[164:167], v[118:121]
	v_mfma_f32_16x16x32_bf16 v[30:33], v[130:133], v[164:167], v[30:33]
	v_mfma_f32_16x16x32_bf16 v[26:29], v[126:129], v[168:171], v[26:29]
	v_mfma_f32_16x16x32_bf16 v[30:33], v[134:137], v[168:171], v[30:33]
	s_setprio 0
	s_barrier
	s_add_i32 s35, s35, s7
	v_lshl_add_u64 v[78:79], v[146:147], 0, s[26:27]
	s_mov_b32 m0, s35
	s_nop 0
	global_load_lds_dwordx4 v[78:79], off
	s_add_i32 m0, s35, 0x2000
	s_add_u32 s68, s44, 0x80080
	v_lshl_add_u64 v[78:79], v[148:149], 0, s[26:27]
	s_addc_u32 s69, s45, 0
	s_add_i32 s35, s41, s7
	global_load_lds_dwordx4 v[78:79], off
	v_lshl_add_u64 v[78:79], s[68:69], 0, v[70:71]
	s_mov_b32 m0, s35
	s_nop 0
	global_load_lds_dwordx4 v[78:79], off
	v_lshl_add_u64 v[78:79], s[68:69], 0, v[66:67]
	s_add_i32 m0, s35, 0x2000
	s_nop 0
	global_load_lds_dwordx4 v[78:79], off
	v_lshl_add_u64 v[78:79], v[172:173], 0, s[26:27]
	s_mov_b32 m0, s22
	s_nop 0
	global_load_lds_dwordx4 v[78:79], off
	v_lshl_add_u64 v[78:79], v[174:175], 0, s[26:27]
	s_mov_b32 m0, s23
	s_nop 0
	global_load_lds_dwordx4 v[78:79], off
	s_waitcnt vmcnt(8)
	s_waitcnt lgkmcnt(0)
	s_barrier
	s_setprio 1
	s_setprio 0
	s_setprio 1
	s_setprio 0
	s_barrier
	s_andn2_b64 vcc, exec, s[48:49]
	s_cbranch_vccnz .LBB0_171
	s_barrier

; #define PG8_STAGE(bufoff, gbase, voff) do { _Pragma("unroll") for (int _i = 0; _i < 2; ++_i) \
;         __builtin_amdgcn_global_load_lds((const unsigned*)((const char*)(gbase) + (voff)[_i]), (PG8_LAS unsigned*)(lds + (bufoff) + ldsw + _i * 8192), 16, 0, 0); } while (0)
; #define PG8_LDA(dst, b, h) do { _Pragma("unroll") for (int m = 0; m < 4; ++m) _Pragma("unroll") for (int k = 0; k < 2; ++k) dst[m][k] = *(const PG8_LAS bf16x8*)(lds + PG8_SA(b, h) + aoff + m * 2048 + k * 1024); } while (0)
; #define PG8_LDB(dst, b, h) do { _Pragma("unroll") for (int n = 0; n < 2; ++n) _Pragma("unroll") for (int k = 0; k < 2; ++k) dst[n][k] = *(const PG8_LAS bf16x8*)(lds + PG8_SB(b, h) + boff + n * 2048 + k * 1024); } while (0)
; #define PG8_MMA(ai, bj, At, Bt) do { __builtin_amdgcn_s_setprio(1); _Pragma("unroll") for (int m = 0; m < 4; ++m) _Pragma("unroll") for (int n = 0; n < 2; ++n) _Pragma("unroll") for (int k = 0; k < 2; ++k) \
;         acc[ai][bj][m][n] = __builtin_amdgcn_mfma_f32_16x16x32_bf16(Bt[n][k], At[m][k], acc[ai][bj][m][n], 0, 0, 0); __builtin_amdgcn_s_setprio(0); } while (0)
; template <class Epi, class Sched, bool ALIGN_EPI = false, bool SP2 = false>
; __device__ __forceinline__ void gemm_phase(PG8_LAS unsigned char* lds, const Gemm g, const Sched& S, const Epi& E, const int wv) {
;     ...
;             if constexpr (SP2) {
;             PG8_LDB(B0, 0, 0); PG8_LDB(B1, 0, 1); PG8_SCHED; PG8_LDA(At, 0, 0); PG8_STAGE(PG8_SA(1, 1), a1 + hstep, voffA);
;             PG8_WAIT_V(8); PG8_WAIT_L(0); PG8_BAR; PG8_MMA(0, 0, At, B0); PG8_MMA(0, 1, At, B1); PG8_BAR; PG8_SCHED;
;             PG8_LDA(At, 0, 1); PG8_STAGE(PG8_SB(0, 0), b2, voffB); PG8_STAGE(PG8_SB(0, 1), b2 + hstep, voffB); PG8_STAGE(PG8_SA(0, 0), a2, voffA);
;             PG8_WAIT_V(8); PG8_WAIT_L(0); PG8_BAR; PG8_MMA(1, 0, At, B0); PG8_MMA(1, 1, At, B1); PG8_BAR; PG8_SCHED;
;             PG8_LDB(B0, 1, 0); PG8_LDB(B1, 1, 1); PG8_SCHED; PG8_LDA(At, 1, 0); PG8_STAGE(PG8_SA(0, 1), a2 + hstep, voffA);
;             PG8_WAIT_V(8); PG8_WAIT_L(0); PG8_BAR; PG8_MMA(0, 0, At, B0); PG8_MMA(0, 1, At, B1); PG8_BAR; PG8_SCHED;
;             PG8_LDA(At, 1, 1); PG8_STAGE(PG8_SB(1, 0), b3, voffB); PG8_STAGE(PG8_SB(1, 1), b3 + hstep, voffB); PG8_STAGE(PG8_SA(1, 0), a3, voffA);
;             PG8_WAIT_V(8); PG8_WAIT_L(0); PG8_BAR; PG8_MMA(1, 0, At, B0); PG8_MMA(1, 1, At, B1); PG8_BAR; PG8_SCHED;
.LBB0_957:
	s_add_u32 s84, s0, 0xfff80080
	s_addc_u32 s85, s1, -1
	s_add_i32 s89, 0, 0x10000
	s_cmp_eq_u32 s88, 28
	s_cselect_b32 s87, s34, s85
	s_cselect_b32 s86, s35, s84
	v_add_u32_e32 v0, s89, v190
	s_cselect_b32 s85, s43, s83
	s_cselect_b32 s84, s75, s77
	s_add_i32 vcc_lo, 0, 0x14000
	ds_read_b128 v[166:169], v0
	ds_read_b128 v[170:173], v0 offset:1024
	ds_read_b128 v[174:177], v0 offset:2048
	ds_read_b128 v[194:197], v0 offset:3072
	v_add_u32_e32 v0, vcc_lo, v190
	ds_read_b128 v[198:201], v0
	ds_read_b128 v[202:205], v0 offset:1024
	ds_read_b128 v[206:209], v0 offset:2048
	ds_read_b128 v[210:213], v0 offset:3072
	v_lshl_add_u64 v[178:179], s[0:1], 0, v[164:165]
	s_add_i32 m0, s66, 0xc000
	ds_read_b128 v[214:217], v192
	ds_read_b128 v[218:221], v192 offset:1024
	ds_read_b128 v[222:225], v192 offset:2048
	ds_read_b128 v[226:229], v192 offset:3072
	ds_read_b128 v[230:233], v192 offset:4096
	ds_read_b128 v[234:237], v192 offset:5120
	ds_read_b128 v[238:241], v192 offset:6144
	ds_read_b128 v[242:245], v192 offset:7168
	global_load_lds_dwordx4 v[178:179], off
	v_lshl_add_u64 v[178:179], s[0:1], 0, v[162:163]
	s_add_i32 m0, s66, 0xe000
	s_nop 0
	global_load_lds_dwordx4 v[178:179], off
	s_waitcnt vmcnt(8)
	s_waitcnt lgkmcnt(0)
	s_setprio 1
	s_barrier
	v_mfma_f32_16x16x32_bf16 v[126:129], v[166:169], v[214:217], v[126:129]
	v_mfma_f32_16x16x32_bf16 v[122:125], v[174:177], v[214:217], v[122:125]
	v_mfma_f32_16x16x32_bf16 v[110:113], v[166:169], v[222:225], v[110:113]
	v_mfma_f32_16x16x32_bf16 v[106:109], v[174:177], v[222:225], v[106:109]
	v_mfma_f32_16x16x32_bf16 v[94:97], v[166:169], v[230:233], v[94:97]
	v_mfma_f32_16x16x32_bf16 v[90:93], v[174:177], v[230:233], v[90:93]
	v_mfma_f32_16x16x32_bf16 v[78:81], v[166:169], v[238:241], v[78:81]
	v_mfma_f32_16x16x32_bf16 v[74:77], v[174:177], v[238:241], v[74:77]
	v_mfma_f32_16x16x32_bf16 v[126:129], v[170:173], v[218:221], v[126:129]
	v_mfma_f32_16x16x32_bf16 v[122:125], v[194:197], v[218:221], v[122:125]
	v_mfma_f32_16x16x32_bf16 v[110:113], v[170:173], v[226:229], v[110:113]
	v_mfma_f32_16x16x32_bf16 v[106:109], v[194:197], v[226:229], v[106:109]
	v_mfma_f32_16x16x32_bf16 v[94:97], v[170:173], v[234:237], v[94:97]
	v_mfma_f32_16x16x32_bf16 v[90:93], v[194:197], v[234:237], v[90:93]
	v_mfma_f32_16x16x32_bf16 v[78:81], v[170:173], v[242:245], v[78:81]
	v_mfma_f32_16x16x32_bf16 v[74:77], v[194:197], v[242:245], v[74:77]
	v_mfma_f32_16x16x32_bf16 v[118:121], v[198:201], v[214:217], v[118:121]
	v_mfma_f32_16x16x32_bf16 v[114:117], v[206:209], v[214:217], v[114:117]
	v_mfma_f32_16x16x32_bf16 v[102:105], v[198:201], v[222:225], v[102:105]
	v_mfma_f32_16x16x32_bf16 v[98:101], v[206:209], v[222:225], v[98:101]
	v_mfma_f32_16x16x32_bf16 v[86:89], v[198:201], v[230:233], v[86:89]
	v_mfma_f32_16x16x32_bf16 v[82:85], v[206:209], v[230:233], v[82:85]
	v_mfma_f32_16x16x32_bf16 v[70:73], v[198:201], v[238:241], v[70:73]
	v_mfma_f32_16x16x32_bf16 v[66:69], v[206:209], v[238:241], v[66:69]
	v_mfma_f32_16x16x32_bf16 v[118:121], v[202:205], v[218:221], v[118:121]
	v_mfma_f32_16x16x32_bf16 v[114:117], v[210:213], v[218:221], v[114:117]
	v_mfma_f32_16x16x32_bf16 v[102:105], v[202:205], v[226:229], v[102:105]
	v_mfma_f32_16x16x32_bf16 v[98:101], v[210:213], v[226:229], v[98:101]
	v_mfma_f32_16x16x32_bf16 v[86:89], v[202:205], v[234:237], v[86:89]
	v_mfma_f32_16x16x32_bf16 v[82:85], v[210:213], v[234:237], v[82:85]
	v_mfma_f32_16x16x32_bf16 v[70:73], v[202:205], v[242:245], v[70:73]
	v_mfma_f32_16x16x32_bf16 v[66:69], v[210:213], v[242:245], v[66:69]
	s_setprio 0
	s_barrier
	s_add_i32 s89, s89, s57
	v_lshl_add_u64 v[178:179], s[84:85], 0, v[132:133]
	s_mov_b32 m0, s89
	ds_read_b128 v[214:217], v192 offset:16384
	ds_read_b128 v[218:221], v192 offset:17408
	ds_read_b128 v[222:225], v192 offset:18432
	ds_read_b128 v[226:229], v192 offset:19456
	ds_read_b128 v[230:233], v192 offset:20480
	ds_read_b128 v[234:237], v192 offset:21504
	ds_read_b128 v[238:241], v192 offset:22528
	ds_read_b128 v[242:245], v192 offset:23552
	global_load_lds_dwordx4 v[178:179], off
	s_add_i32 m0, s89, 0x2000
	s_add_u32 s90, s84, 0x80000
	v_lshl_add_u64 v[246:247], s[84:85], 0, v[136:137]
	s_addc_u32 s91, s85, 0
	s_add_i32 s89, vcc_lo, s57
	global_load_lds_dwordx4 v[246:247], off
	v_lshl_add_u64 v[248:249], s[90:91], 0, v[132:133]
	s_mov_b32 m0, s89
	v_lshl_add_u64 v[146:147], s[86:87], 0, v[134:135]
	global_load_lds_dwordx4 v[248:249], off
	v_lshl_add_u64 v[248:249], s[90:91], 0, v[136:137]
	s_add_i32 m0, s89, 0x2000
	s_nop 0
	global_load_lds_dwordx4 v[248:249], off
	v_lshl_add_u64 v[248:249], s[86:87], 0, v[130:131]
	s_mov_b32 m0, s66
	s_nop 0
	global_load_lds_dwordx4 v[248:249], off
	s_mov_b32 m0, s61
	s_nop 0
	global_load_lds_dwordx4 v[146:147], off
	s_waitcnt vmcnt(8)
	s_waitcnt lgkmcnt(0)
	s_setprio 1
	s_barrier
; #define PG8_STAGE(bufoff, gbase, voff) do { _Pragma("unroll") for (int _i = 0; _i < 2; ++_i) \
;         __builtin_amdgcn_global_load_lds((const unsigned*)((const char*)(gbase) + (voff)[_i]), (PG8_LAS unsigned*)(lds + (bufoff) + ldsw + _i * 8192), 16, 0, 0); } while (0)
; #define PG8_LDA(dst, b, h) do { _Pragma("unroll") for (int m = 0; m < 4; ++m) _Pragma("unroll") for (int k = 0; k < 2; ++k) dst[m][k] = *(const PG8_LAS bf16x8*)(lds + PG8_SA(b, h) + aoff + m * 2048 + k * 1024); } while (0)
; #define PG8_LDB(dst, b, h) do { _Pragma("unroll") for (int n = 0; n < 2; ++n) _Pragma("unroll") for (int k = 0; k < 2; ++k) dst[n][k] = *(const PG8_LAS bf16x8*)(lds + PG8_SB(b, h) + boff + n * 2048 + k * 1024); } while (0)
; #define PG8_MMA(ai, bj, At, Bt) do { __builtin_amdgcn_s_setprio(1); _Pragma("unroll") for (int m = 0; m < 4; ++m) _Pragma("unroll") for (int n = 0; n < 2; ++n) _Pragma("unroll") for (int k = 0; k < 2; ++k) \
;         acc[ai][bj][m][n] = __builtin_amdgcn_mfma_f32_16x16x32_bf16(Bt[n][k], At[m][k], acc[ai][bj][m][n], 0, 0, 0); __builtin_amdgcn_s_setprio(0); } while (0)
; template <class Epi, class Sched, bool ALIGN_EPI = false, bool SP2 = false>
; __device__ __forceinline__ void gemm_phase(PG8_LAS unsigned char* lds, const Gemm g, const Sched& S, const Epi& E, const int wv) {
;     ...
;             if constexpr (SP2) {
;             PG8_LDB(B0, 0, 0); PG8_LDB(B1, 0, 1); PG8_SCHED; PG8_LDA(At, 0, 0); PG8_STAGE(PG8_SA(1, 1), a1 + hstep, voffA);
;             PG8_WAIT_V(8); PG8_WAIT_L(0); PG8_BAR; PG8_MMA(0, 0, At, B0); PG8_MMA(0, 1, At, B1); PG8_BAR; PG8_SCHED;
;             PG8_LDA(At, 0, 1); PG8_STAGE(PG8_SB(0, 0), b2, voffB); PG8_STAGE(PG8_SB(0, 1), b2 + hstep, voffB); PG8_STAGE(PG8_SA(0, 0), a2, voffA);
;             PG8_WAIT_V(8); PG8_WAIT_L(0); PG8_BAR; PG8_MMA(1, 0, At, B0); PG8_MMA(1, 1, At, B1); PG8_BAR; PG8_SCHED;
;             PG8_LDB(B0, 1, 0); PG8_LDB(B1, 1, 1); PG8_SCHED; PG8_LDA(At, 1, 0); PG8_STAGE(PG8_SA(0, 1), a2 + hstep, voffA);
;             PG8_WAIT_V(8); PG8_WAIT_L(0); PG8_BAR; PG8_MMA(0, 0, At, B0); PG8_MMA(0, 1, At, B1); PG8_BAR; PG8_SCHED;
;             PG8_LDA(At, 1, 1); PG8_STAGE(PG8_SB(1, 0), b3, voffB); PG8_STAGE(PG8_SB(1, 1), b3 + hstep, voffB); PG8_STAGE(PG8_SA(1, 0), a3, voffA);
;             PG8_WAIT_V(8); PG8_WAIT_L(0); PG8_BAR; PG8_MMA(1, 0, At, B0); PG8_MMA(1, 1, At, B1); PG8_BAR; PG8_SCHED;
	v_mfma_f32_16x16x32_bf16 v[62:65], v[166:169], v[214:217], v[62:65]
	v_mfma_f32_16x16x32_bf16 v[58:61], v[174:177], v[214:217], v[58:61]
	v_mfma_f32_16x16x32_bf16 v[46:49], v[166:169], v[222:225], v[46:49]
	v_mfma_f32_16x16x32_bf16 v[42:45], v[174:177], v[222:225], v[42:45]
	v_mfma_f32_16x16x32_bf16 v[30:33], v[166:169], v[230:233], v[30:33]
	v_mfma_f32_16x16x32_bf16 v[26:29], v[174:177], v[230:233], v[26:29]
	v_mfma_f32_16x16x32_bf16 v[14:17], v[166:169], v[238:241], v[14:17]
	v_mfma_f32_16x16x32_bf16 v[10:13], v[174:177], v[238:241], v[10:13]
	v_mfma_f32_16x16x32_bf16 v[62:65], v[170:173], v[218:221], v[62:65]
	v_mfma_f32_16x16x32_bf16 v[58:61], v[194:197], v[218:221], v[58:61]
	v_mfma_f32_16x16x32_bf16 v[46:49], v[170:173], v[226:229], v[46:49]
	v_mfma_f32_16x16x32_bf16 v[42:45], v[194:197], v[226:229], v[42:45]
	v_mfma_f32_16x16x32_bf16 v[30:33], v[170:173], v[234:237], v[30:33]
	v_mfma_f32_16x16x32_bf16 v[26:29], v[194:197], v[234:237], v[26:29]
	v_mfma_f32_16x16x32_bf16 v[14:17], v[170:173], v[242:245], v[14:17]
	v_mfma_f32_16x16x32_bf16 v[10:13], v[194:197], v[242:245], v[10:13]
	v_mfma_f32_16x16x32_bf16 v[54:57], v[198:201], v[214:217], v[54:57]
	v_mfma_f32_16x16x32_bf16 v[50:53], v[206:209], v[214:217], v[50:53]
	v_mfma_f32_16x16x32_bf16 v[38:41], v[198:201], v[222:225], v[38:41]
	v_mfma_f32_16x16x32_bf16 v[34:37], v[206:209], v[222:225], v[34:37]
	v_mfma_f32_16x16x32_bf16 v[22:25], v[198:201], v[230:233], v[22:25]
	v_mfma_f32_16x16x32_bf16 v[18:21], v[206:209], v[230:233], v[18:21]
	v_mfma_f32_16x16x32_bf16 v[6:9], v[198:201], v[238:241], v[6:9]
	v_mfma_f32_16x16x32_bf16 v[2:5], v[206:209], v[238:241], v[2:5]
	v_mfma_f32_16x16x32_bf16 v[54:57], v[202:205], v[218:221], v[54:57]
	v_mfma_f32_16x16x32_bf16 v[50:53], v[210:213], v[218:221], v[50:53]
	v_mfma_f32_16x16x32_bf16 v[38:41], v[202:205], v[226:229], v[38:41]
	v_mfma_f32_16x16x32_bf16 v[34:37], v[210:213], v[226:229], v[34:37]
	v_mfma_f32_16x16x32_bf16 v[22:25], v[202:205], v[234:237], v[22:25]
	v_mfma_f32_16x16x32_bf16 v[18:21], v[210:213], v[234:237], v[18:21]
	v_mfma_f32_16x16x32_bf16 v[6:9], v[202:205], v[242:245], v[6:9]
	v_mfma_f32_16x16x32_bf16 v[2:5], v[210:213], v[242:245], v[2:5]
	s_setprio 0
	s_barrier
	s_add_i32 s89, 0, 0x18000
	v_add_u32_e32 v0, s89, v190
	s_add_i32 s90, 0, 0x1c000
	ds_read_b128 v[166:169], v0
	ds_read_b128 v[170:173], v0 offset:1024
	ds_read_b128 v[174:177], v0 offset:2048
	ds_read_b128 v[194:197], v0 offset:3072
	v_add_u32_e32 v0, s90, v190
	ds_read_b128 v[198:201], v0
	ds_read_b128 v[202:205], v0 offset:1024
	ds_read_b128 v[206:209], v0 offset:2048
	ds_read_b128 v[210:213], v0 offset:3072
	s_add_u32 s86, s86, 0x80000
	s_addc_u32 s87, s87, 0
	s_mov_b32 m0, s62
	v_lshl_add_u64 v[148:149], s[86:87], 0, v[130:131]
	ds_read_b128 v[214:217], v192 offset:32768
	ds_read_b128 v[218:221], v192 offset:33792
	ds_read_b128 v[222:225], v192 offset:34816
	ds_read_b128 v[226:229], v192 offset:35840
	ds_read_b128 v[230:233], v192 offset:36864
	ds_read_b128 v[234:237], v192 offset:37888
	ds_read_b128 v[238:241], v192 offset:38912
	ds_read_b128 v[242:245], v192 offset:39936
	global_load_lds_dwordx4 v[148:149], off
	v_lshl_add_u64 v[148:149], s[86:87], 0, v[134:135]
	s_mov_b32 m0, s58
	s_nop 0
	global_load_lds_dwordx4 v[148:149], off
	s_waitcnt vmcnt(8)
	s_waitcnt lgkmcnt(0)
	s_setprio 1
	s_barrier
	v_mfma_f32_16x16x32_bf16 v[126:129], v[166:169], v[214:217], v[126:129]
	v_mfma_f32_16x16x32_bf16 v[122:125], v[174:177], v[214:217], v[122:125]
	v_mfma_f32_16x16x32_bf16 v[110:113], v[166:169], v[222:225], v[110:113]
	v_mfma_f32_16x16x32_bf16 v[106:109], v[174:177], v[222:225], v[106:109]
	v_mfma_f32_16x16x32_bf16 v[94:97], v[166:169], v[230:233], v[94:97]
	v_mfma_f32_16x16x32_bf16 v[90:93], v[174:177], v[230:233], v[90:93]
	v_mfma_f32_16x16x32_bf16 v[78:81], v[166:169], v[238:241], v[78:81]
	v_mfma_f32_16x16x32_bf16 v[74:77], v[174:177], v[238:241], v[74:77]
	v_mfma_f32_16x16x32_bf16 v[126:129], v[170:173], v[218:221], v[126:129]
	v_mfma_f32_16x16x32_bf16 v[122:125], v[194:197], v[218:221], v[122:125]
	v_mfma_f32_16x16x32_bf16 v[110:113], v[170:173], v[226:229], v[110:113]
	v_mfma_f32_16x16x32_bf16 v[106:109], v[194:197], v[226:229], v[106:109]
	v_mfma_f32_16x16x32_bf16 v[94:97], v[170:173], v[234:237], v[94:97]
	v_mfma_f32_16x16x32_bf16 v[90:93], v[194:197], v[234:237], v[90:93]
	v_mfma_f32_16x16x32_bf16 v[78:81], v[170:173], v[242:245], v[78:81]
	v_mfma_f32_16x16x32_bf16 v[74:77], v[194:197], v[242:245], v[74:77]
	v_mfma_f32_16x16x32_bf16 v[118:121], v[198:201], v[214:217], v[118:121]
	v_mfma_f32_16x16x32_bf16 v[114:117], v[206:209], v[214:217], v[114:117]
	v_mfma_f32_16x16x32_bf16 v[102:105], v[198:201], v[222:225], v[102:105]
	v_mfma_f32_16x16x32_bf16 v[98:101], v[206:209], v[222:225], v[98:101]
	v_mfma_f32_16x16x32_bf16 v[86:89], v[198:201], v[230:233], v[86:89]
	v_mfma_f32_16x16x32_bf16 v[82:85], v[206:209], v[230:233], v[82:85]
	v_mfma_f32_16x16x32_bf16 v[70:73], v[198:201], v[238:241], v[70:73]
	v_mfma_f32_16x16x32_bf16 v[66:69], v[206:209], v[238:241], v[66:69]
	v_mfma_f32_16x16x32_bf16 v[118:121], v[202:205], v[218:221], v[118:121]
	v_mfma_f32_16x16x32_bf16 v[114:117], v[210:213], v[218:221], v[114:117]
	v_mfma_f32_16x16x32_bf16 v[102:105], v[202:205], v[226:229], v[102:105]
	v_mfma_f32_16x16x32_bf16 v[98:101], v[210:213], v[226:229], v[98:101]
	v_mfma_f32_16x16x32_bf16 v[86:89], v[202:205], v[234:237], v[86:89]
	v_mfma_f32_16x16x32_bf16 v[82:85], v[210:213], v[234:237], v[82:85]
	v_mfma_f32_16x16x32_bf16 v[70:73], v[202:205], v[242:245], v[70:73]
	v_mfma_f32_16x16x32_bf16 v[66:69], v[210:213], v[242:245], v[66:69]
	s_setprio 0
	s_barrier
; #define PG8_STAGE(bufoff, gbase, voff) do { _Pragma("unroll") for (int _i = 0; _i < 2; ++_i) \
;         __builtin_amdgcn_global_load_lds((const unsigned*)((const char*)(gbase) + (voff)[_i]), (PG8_LAS unsigned*)(lds + (bufoff) + ldsw + _i * 8192), 16, 0, 0); } while (0)
; #define PG8_LDA(dst, b, h) do { _Pragma("unroll") for (int m = 0; m < 4; ++m) _Pragma("unroll") for (int k = 0; k < 2; ++k) dst[m][k] = *(const PG8_LAS bf16x8*)(lds + PG8_SA(b, h) + aoff + m * 2048 + k * 1024); } while (0)
; #define PG8_LDB(dst, b, h) do { _Pragma("unroll") for (int n = 0; n < 2; ++n) _Pragma("unroll") for (int k = 0; k < 2; ++k) dst[n][k] = *(const PG8_LAS bf16x8*)(lds + PG8_SB(b, h) + boff + n * 2048 + k * 1024); } while (0)
; #define PG8_MMA(ai, bj, At, Bt) do { __builtin_amdgcn_s_setprio(1); _Pragma("unroll") for (int m = 0; m < 4; ++m) _Pragma("unroll") for (int n = 0; n < 2; ++n) _Pragma("unroll") for (int k = 0; k < 2; ++k) \
;         acc[ai][bj][m][n] = __builtin_amdgcn_mfma_f32_16x16x32_bf16(Bt[n][k], At[m][k], acc[ai][bj][m][n], 0, 0, 0); __builtin_amdgcn_s_setprio(0); } while (0)
; template <class Epi, class Sched, bool ALIGN_EPI = false, bool SP2 = false>
; __device__ __forceinline__ void gemm_phase(PG8_LAS unsigned char* lds, const Gemm g, const Sched& S, const Epi& E, const int wv) {
;     ...
;             if constexpr (SP2) {
;             PG8_LDB(B0, 0, 0); PG8_LDB(B1, 0, 1); PG8_SCHED; PG8_LDA(At, 0, 0); PG8_STAGE(PG8_SA(1, 1), a1 + hstep, voffA);
;             PG8_WAIT_V(8); PG8_WAIT_L(0); PG8_BAR; PG8_MMA(0, 0, At, B0); PG8_MMA(0, 1, At, B1); PG8_BAR; PG8_SCHED;
;             PG8_LDA(At, 0, 1); PG8_STAGE(PG8_SB(0, 0), b2, voffB); PG8_STAGE(PG8_SB(0, 1), b2 + hstep, voffB); PG8_STAGE(PG8_SA(0, 0), a2, voffA);
;             PG8_WAIT_V(8); PG8_WAIT_L(0); PG8_BAR; PG8_MMA(1, 0, At, B0); PG8_MMA(1, 1, At, B1); PG8_BAR; PG8_SCHED;
;             PG8_LDB(B0, 1, 0); PG8_LDB(B1, 1, 1); PG8_SCHED; PG8_LDA(At, 1, 0); PG8_STAGE(PG8_SA(0, 1), a2 + hstep, voffA);
;             PG8_WAIT_V(8); PG8_WAIT_L(0); PG8_BAR; PG8_MMA(0, 0, At, B0); PG8_MMA(0, 1, At, B1); PG8_BAR; PG8_SCHED;
;             PG8_LDA(At, 1, 1); PG8_STAGE(PG8_SB(1, 0), b3, voffB); PG8_STAGE(PG8_SB(1, 1), b3 + hstep, voffB); PG8_STAGE(PG8_SA(1, 0), a3, voffA);
;             PG8_WAIT_V(8); PG8_WAIT_L(0); PG8_BAR; PG8_MMA(1, 0, At, B0); PG8_MMA(1, 1, At, B1); PG8_BAR; PG8_SCHED;
	s_add_i32 s86, s89, s57
	v_lshl_add_u64 v[148:149], v[178:179], 0, s[26:27]
	s_mov_b32 m0, s86
	ds_read_b128 v[214:217], v192 offset:49152
	ds_read_b128 v[218:221], v192 offset:50176
	ds_read_b128 v[222:225], v192 offset:51200
	ds_read_b128 v[226:229], v192 offset:52224
	ds_read_b128 v[230:233], v192 offset:53248
	ds_read_b128 v[234:237], v192 offset:54272
	ds_read_b128 v[238:241], v192 offset:55296
	ds_read_b128 v[242:245], v192 offset:56320
	global_load_lds_dwordx4 v[148:149], off
	s_add_i32 m0, s86, 0x2000
	s_add_u32 s84, s84, 0x80080
	v_lshl_add_u64 v[148:149], v[246:247], 0, s[26:27]
	s_addc_u32 s85, s85, 0
	s_add_i32 s86, s90, s57
	global_load_lds_dwordx4 v[148:149], off
	v_lshl_add_u64 v[148:149], s[84:85], 0, v[132:133]
	s_mov_b32 m0, s86
	v_lshl_add_u64 v[146:147], v[146:147], 0, s[26:27]
	global_load_lds_dwordx4 v[148:149], off
	v_lshl_add_u64 v[148:149], s[84:85], 0, v[136:137]
	s_add_i32 m0, s86, 0x2000
	s_nop 0
	global_load_lds_dwordx4 v[148:149], off
	v_lshl_add_u64 v[148:149], v[248:249], 0, s[26:27]
	s_mov_b32 m0, s7
	s_nop 0
	global_load_lds_dwordx4 v[148:149], off
	s_mov_b32 m0, s22
	s_nop 0
	global_load_lds_dwordx4 v[146:147], off
	s_waitcnt vmcnt(8)
	s_waitcnt lgkmcnt(0)
	s_setprio 1
	s_barrier
	v_mfma_f32_16x16x32_bf16 v[62:65], v[166:169], v[214:217], v[62:65]
	v_mfma_f32_16x16x32_bf16 v[58:61], v[174:177], v[214:217], v[58:61]
	v_mfma_f32_16x16x32_bf16 v[46:49], v[166:169], v[222:225], v[46:49]
	v_mfma_f32_16x16x32_bf16 v[42:45], v[174:177], v[222:225], v[42:45]
	v_mfma_f32_16x16x32_bf16 v[30:33], v[166:169], v[230:233], v[30:33]
	v_mfma_f32_16x16x32_bf16 v[26:29], v[174:177], v[230:233], v[26:29]
	v_mfma_f32_16x16x32_bf16 v[14:17], v[166:169], v[238:241], v[14:17]
	v_mfma_f32_16x16x32_bf16 v[10:13], v[174:177], v[238:241], v[10:13]
	v_mfma_f32_16x16x32_bf16 v[62:65], v[170:173], v[218:221], v[62:65]
	v_mfma_f32_16x16x32_bf16 v[58:61], v[194:197], v[218:221], v[58:61]
	v_mfma_f32_16x16x32_bf16 v[46:49], v[170:173], v[226:229], v[46:49]
	v_mfma_f32_16x16x32_bf16 v[42:45], v[194:197], v[226:229], v[42:45]
	v_mfma_f32_16x16x32_bf16 v[30:33], v[170:173], v[234:237], v[30:33]
	v_mfma_f32_16x16x32_bf16 v[26:29], v[194:197], v[234:237], v[26:29]
	v_mfma_f32_16x16x32_bf16 v[14:17], v[170:173], v[242:245], v[14:17]
	v_mfma_f32_16x16x32_bf16 v[10:13], v[194:197], v[242:245], v[10:13]
	v_mfma_f32_16x16x32_bf16 v[54:57], v[198:201], v[214:217], v[54:57]
	v_mfma_f32_16x16x32_bf16 v[50:53], v[206:209], v[214:217], v[50:53]
	v_mfma_f32_16x16x32_bf16 v[38:41], v[198:201], v[222:225], v[38:41]
	v_mfma_f32_16x16x32_bf16 v[34:37], v[206:209], v[222:225], v[34:37]
	v_mfma_f32_16x16x32_bf16 v[22:25], v[198:201], v[230:233], v[22:25]
	v_mfma_f32_16x16x32_bf16 v[18:21], v[206:209], v[230:233], v[18:21]
	v_mfma_f32_16x16x32_bf16 v[6:9], v[198:201], v[238:241], v[6:9]
	v_mfma_f32_16x16x32_bf16 v[2:5], v[206:209], v[238:241], v[2:5]
	v_mfma_f32_16x16x32_bf16 v[54:57], v[202:205], v[218:221], v[54:57]
	v_mfma_f32_16x16x32_bf16 v[50:53], v[210:213], v[218:221], v[50:53]
	v_mfma_f32_16x16x32_bf16 v[38:41], v[202:205], v[226:229], v[38:41]
	v_mfma_f32_16x16x32_bf16 v[34:37], v[210:213], v[226:229], v[34:37]
	v_mfma_f32_16x16x32_bf16 v[22:25], v[202:205], v[234:237], v[22:25]
	v_mfma_f32_16x16x32_bf16 v[18:21], v[210:213], v[234:237], v[18:21]
	v_mfma_f32_16x16x32_bf16 v[6:9], v[202:205], v[242:245], v[6:9]
	v_mfma_f32_16x16x32_bf16 v[2:5], v[210:213], v[242:245], v[2:5]
	s_setprio 0
	s_barrier
	s_add_i32 s88, s88, 2
	s_add_u32 s77, s77, 0x100
	s_addc_u32 s83, s83, 0
	s_add_u32 s0, s0, 0x100
	s_addc_u32 s1, s1, 0
	s_cmp_gt_u32 s88, 29
	s_cbranch_scc0 .LBB0_957
	s_and_b64 vcc, exec, s[48:49]
	s_cbranch_vccz .LBB0_960
	s_barrier
